# hand-off version with the closing phase barrier signalled two MFMAs early (tail MFMAs at priority 2)
# baseline (speedup 1.0000x reference)
; #define PG8_STAGE(bufoff, gbase, voff) do { _Pragma("unroll") for (int _i = 0; _i < 2; ++_i) \
;         __builtin_amdgcn_global_load_lds((const unsigned*)((const char*)(gbase) + (voff)[_i]), (LAS unsigned*)(lds + (bufoff) + ldsw + _i * 8192), 16, 0, 0); } while (0)
; #define PG8_LDA(dst, b, h) do { _Pragma("unroll") for (int m = 0; m < 4; ++m) _Pragma("unroll") for (int k = 0; k < 2; ++k) dst[m][k] = *(const LAS bf16x8*)(lds + PG8_SA(b, h) + aoff + m * 2048 + k * 1024); } while (0)
; #define PG8_LDB(dst, b, h) do { _Pragma("unroll") for (int n = 0; n < 2; ++n) _Pragma("unroll") for (int k = 0; k < 2; ++k) dst[n][k] = *(const LAS bf16x8*)(lds + PG8_SB(b, h) + boff + n * 2048 + k * 1024); } while (0)
; #define PG8_MMA(ai, bj, At, Bt) do { __builtin_amdgcn_s_setprio(1); _Pragma("unroll") for (int m = 0; m < 4; ++m) _Pragma("unroll") for (int n = 0; n < 2; ++n) _Pragma("unroll") for (int k = 0; k < 2; ++k) \
;         acc[ai][bj][m][n] = __builtin_amdgcn_mfma_f32_16x16x32_bf16(Bt[n][k], At[m][k], acc[ai][bj][m][n], 0, 0, 0); __builtin_amdgcn_s_setprio(0); } while (0)
; #define PG8_WAIT_V(n) asm volatile("s_waitcnt vmcnt(" #n ")" ::: "memory")
; #define PG8_WAIT_L(n) asm volatile("s_waitcnt lgkmcnt(" #n ")" ::: "memory")
; #define PG8_BAR __builtin_amdgcn_s_barrier()
; #define PG8_SCHED __builtin_amdgcn_sched_barrier(0)
; template <class Epi, class Sched>
; __device__ __forceinline__ void gemm_phase(LAS unsigned char* lds, const int K, const Sched& S, const Epi& E) {
;     ...
;             const bool last = (t == nt - 2);
;             const char* a1 = cA + (size_t)(t + 1) * kstep;
;             const char* a2 = last ? nA : cA + (size_t)(t + 2) * kstep; const char* b2 = last ? nB : cB + (size_t)(t + 2) * kstep;
;             const char* a3 = a2 + kstep; const char* b3 = b2 + kstep;
;             PG8_LDB(B0, 0, 0); PG8_LDB(B1, 0, 1); PG8_SCHED; PG8_LDA(At, 0, 0); PG8_STAGE(PG8_SA(1, 1), a1 + hstep, voffA);
;             PG8_WAIT_V(8); PG8_WAIT_L(0); PG8_BAR; PG8_MMA(0, 0, At, B0); PG8_MMA(0, 1, At, B1); PG8_BAR; PG8_SCHED;
;             PG8_LDA(At, 0, 1); PG8_STAGE(PG8_SB(0, 0), b2, voffB); PG8_STAGE(PG8_SB(0, 1), b2 + hstep, voffB); PG8_STAGE(PG8_SA(0, 0), a2, voffA);
;             PG8_WAIT_V(8); PG8_WAIT_L(0); PG8_BAR; PG8_MMA(1, 0, At, B0); PG8_MMA(1, 1, At, B1); PG8_BAR; PG8_SCHED;
.LBB0_403:
	s_add_u32 s14, s8, 0xfffc0080
	s_addc_u32 s15, s9, -1
	s_add_i32 s16, 0, 0x10000
	s_cmp_eq_u32 s13, 12
	s_cselect_b32 s55, s2, s15
	s_cselect_b32 s54, s4, s14
	v_add_u32_e32 v128, s16, v149
	s_cselect_b32 s39, s5, s12
	s_cselect_b32 s38, s10, s11
	s_add_i32 s17, 0, 0x14000
	ds_read_b128 v[158:161], v128
	ds_read_b128 v[162:165], v128 offset:1024
	ds_read_b128 v[184:187], v128 offset:2048
	ds_read_b128 v[188:191], v128 offset:3072
	v_add_u32_e32 v128, s17, v149
	ds_read_b128 v[192:195], v128
	ds_read_b128 v[196:199], v128 offset:1024
	ds_read_b128 v[200:203], v128 offset:2048
	ds_read_b128 v[204:207], v128 offset:3072
	v_lshl_add_u64 v[166:167], s[8:9], 0, v[154:155]
	s_add_i32 m0, s59, 0xc000
	ds_read_b128 v[208:211], v147
	ds_read_b128 v[212:215], v147 offset:1024
	ds_read_b128 v[216:219], v147 offset:2048
	ds_read_b128 v[220:223], v147 offset:3072
	ds_read_b128 v[224:227], v147 offset:4096
	ds_read_b128 v[228:231], v147 offset:5120
	ds_read_b128 v[232:235], v147 offset:6144
	ds_read_b128 v[236:239], v147 offset:7168
	global_load_lds_dwordx4 v[166:167], off
	v_lshl_add_u64 v[166:167], s[8:9], 0, v[156:157]
	s_add_i32 m0, s59, 0xe000
	s_nop 0
	global_load_lds_dwordx4 v[166:167], off
	s_waitcnt vmcnt(8)
	s_waitcnt lgkmcnt(0)
	s_setprio 1
	s_barrier
	v_mfma_f32_16x16x32_bf16 v[124:127], v[158:161], v[208:211], v[124:127]
	v_mfma_f32_16x16x32_bf16 v[120:123], v[184:187], v[208:211], v[120:123]
	v_mfma_f32_16x16x32_bf16 v[108:111], v[158:161], v[216:219], v[108:111]
	v_mfma_f32_16x16x32_bf16 v[104:107], v[184:187], v[216:219], v[104:107]
	v_mfma_f32_16x16x32_bf16 v[92:95], v[158:161], v[224:227], v[92:95]
	v_mfma_f32_16x16x32_bf16 v[88:91], v[184:187], v[224:227], v[88:91]
	v_mfma_f32_16x16x32_bf16 v[76:79], v[158:161], v[232:235], v[76:79]
	v_mfma_f32_16x16x32_bf16 v[72:75], v[184:187], v[232:235], v[72:75]
	v_mfma_f32_16x16x32_bf16 v[124:127], v[162:165], v[212:215], v[124:127]
	v_mfma_f32_16x16x32_bf16 v[120:123], v[188:191], v[212:215], v[120:123]
	v_mfma_f32_16x16x32_bf16 v[108:111], v[162:165], v[220:223], v[108:111]
	v_mfma_f32_16x16x32_bf16 v[104:107], v[188:191], v[220:223], v[104:107]
	v_mfma_f32_16x16x32_bf16 v[92:95], v[162:165], v[228:231], v[92:95]
	v_mfma_f32_16x16x32_bf16 v[88:91], v[188:191], v[228:231], v[88:91]
	v_mfma_f32_16x16x32_bf16 v[76:79], v[162:165], v[236:239], v[76:79]
	v_mfma_f32_16x16x32_bf16 v[72:75], v[188:191], v[236:239], v[72:75]
	s_setprio 0
	s_setprio 1
	v_mfma_f32_16x16x32_bf16 v[116:119], v[192:195], v[208:211], v[116:119]
	v_mfma_f32_16x16x32_bf16 v[112:115], v[200:203], v[208:211], v[112:115]
	v_mfma_f32_16x16x32_bf16 v[100:103], v[192:195], v[216:219], v[100:103]
	v_mfma_f32_16x16x32_bf16 v[96:99], v[200:203], v[216:219], v[96:99]
	v_mfma_f32_16x16x32_bf16 v[84:87], v[192:195], v[224:227], v[84:87]
	v_mfma_f32_16x16x32_bf16 v[80:83], v[200:203], v[224:227], v[80:83]
	v_mfma_f32_16x16x32_bf16 v[68:71], v[192:195], v[232:235], v[68:71]
	v_mfma_f32_16x16x32_bf16 v[64:67], v[200:203], v[232:235], v[64:67]
	v_mfma_f32_16x16x32_bf16 v[116:119], v[196:199], v[212:215], v[116:119]
	v_mfma_f32_16x16x32_bf16 v[112:115], v[204:207], v[212:215], v[112:115]
	v_mfma_f32_16x16x32_bf16 v[100:103], v[196:199], v[220:223], v[100:103]
	v_mfma_f32_16x16x32_bf16 v[96:99], v[204:207], v[220:223], v[96:99]
	v_mfma_f32_16x16x32_bf16 v[84:87], v[196:199], v[228:231], v[84:87]
	v_mfma_f32_16x16x32_bf16 v[80:83], v[204:207], v[228:231], v[80:83]
	s_setprio 2
	s_barrier
	v_mfma_f32_16x16x32_bf16 v[68:71], v[196:199], v[236:239], v[68:71]
	v_mfma_f32_16x16x32_bf16 v[64:67], v[204:207], v[236:239], v[64:67]
	s_setprio 0
	s_add_i32 s14, s16, s58
	v_lshl_add_u64 v[166:167], s[38:39], 0, v[140:141]
	s_mov_b32 m0, s14
	ds_read_b128 v[208:211], v147 offset:16384
	ds_read_b128 v[212:215], v147 offset:17408
	ds_read_b128 v[216:219], v147 offset:18432
	ds_read_b128 v[220:223], v147 offset:19456
	ds_read_b128 v[224:227], v147 offset:20480
	ds_read_b128 v[228:231], v147 offset:21504
	ds_read_b128 v[232:235], v147 offset:22528
	ds_read_b128 v[236:239], v147 offset:23552
	global_load_lds_dwordx4 v[166:167], off
	s_add_i32 m0, s14, 0x2000
	s_add_u32 s14, s38, 0x40000
	v_lshl_add_u64 v[180:181], s[38:39], 0, v[144:145]
	s_addc_u32 s15, s39, 0
	s_add_i32 s16, s17, s58
	global_load_lds_dwordx4 v[180:181], off
	v_lshl_add_u64 v[182:183], s[14:15], 0, v[140:141]
	s_mov_b32 m0, s16
	v_lshl_add_u64 v[240:241], s[54:55], 0, v[142:143]
	global_load_lds_dwordx4 v[182:183], off
	v_lshl_add_u64 v[182:183], s[14:15], 0, v[144:145]
	s_add_i32 m0, s16, 0x2000
	s_nop 0
	global_load_lds_dwordx4 v[182:183], off
	v_lshl_add_u64 v[182:183], s[54:55], 0, v[138:139]
	s_mov_b32 m0, s59
	s_nop 0
	global_load_lds_dwordx4 v[182:183], off
	s_mov_b32 m0, s60
	s_nop 0
	global_load_lds_dwordx4 v[240:241], off
	s_waitcnt vmcnt(8)
	s_waitcnt lgkmcnt(0)
	s_setprio 1
	s_barrier
; #define PG8_STAGE(bufoff, gbase, voff) do { _Pragma("unroll") for (int _i = 0; _i < 2; ++_i) \
;         __builtin_amdgcn_global_load_lds((const unsigned*)((const char*)(gbase) + (voff)[_i]), (LAS unsigned*)(lds + (bufoff) + ldsw + _i * 8192), 16, 0, 0); } while (0)
; #define PG8_LDA(dst, b, h) do { _Pragma("unroll") for (int m = 0; m < 4; ++m) _Pragma("unroll") for (int k = 0; k < 2; ++k) dst[m][k] = *(const LAS bf16x8*)(lds + PG8_SA(b, h) + aoff + m * 2048 + k * 1024); } while (0)
; #define PG8_LDB(dst, b, h) do { _Pragma("unroll") for (int n = 0; n < 2; ++n) _Pragma("unroll") for (int k = 0; k < 2; ++k) dst[n][k] = *(const LAS bf16x8*)(lds + PG8_SB(b, h) + boff + n * 2048 + k * 1024); } while (0)
; #define PG8_MMA(ai, bj, At, Bt) do { __builtin_amdgcn_s_setprio(1); _Pragma("unroll") for (int m = 0; m < 4; ++m) _Pragma("unroll") for (int n = 0; n < 2; ++n) _Pragma("unroll") for (int k = 0; k < 2; ++k) \
;         acc[ai][bj][m][n] = __builtin_amdgcn_mfma_f32_16x16x32_bf16(Bt[n][k], At[m][k], acc[ai][bj][m][n], 0, 0, 0); __builtin_amdgcn_s_setprio(0); } while (0)
; #define PG8_WAIT_V(n) asm volatile("s_waitcnt vmcnt(" #n ")" ::: "memory")
; #define PG8_WAIT_L(n) asm volatile("s_waitcnt lgkmcnt(" #n ")" ::: "memory")
; #define PG8_BAR __builtin_amdgcn_s_barrier()
; #define PG8_SCHED __builtin_amdgcn_sched_barrier(0)
; template <class Epi, class Sched>
; __device__ __forceinline__ void gemm_phase(LAS unsigned char* lds, const int K, const Sched& S, const Epi& E) {
;     ...
;             PG8_WAIT_V(8); PG8_WAIT_L(0); PG8_BAR; PG8_MMA(1, 0, At, B0); PG8_MMA(1, 1, At, B1); PG8_BAR; PG8_SCHED;
;             PG8_LDB(B0, 1, 0); PG8_LDB(B1, 1, 1); PG8_SCHED; PG8_LDA(At, 1, 0); PG8_STAGE(PG8_SA(0, 1), a2 + hstep, voffA);
;             PG8_WAIT_V(8); PG8_WAIT_L(0); PG8_BAR; PG8_MMA(0, 0, At, B0); PG8_MMA(0, 1, At, B1); PG8_BAR; PG8_SCHED;
;             PG8_LDA(At, 1, 1); PG8_STAGE(PG8_SB(1, 0), b3, voffB); PG8_STAGE(PG8_SB(1, 1), b3 + hstep, voffB); PG8_STAGE(PG8_SA(1, 0), a3, voffA);
;             PG8_WAIT_V(8); PG8_WAIT_L(0); PG8_BAR; PG8_MMA(1, 0, At, B0); PG8_MMA(1, 1, At, B1); PG8_BAR; PG8_SCHED;
	v_mfma_f32_16x16x32_bf16 v[60:63], v[158:161], v[208:211], v[60:63]
	v_mfma_f32_16x16x32_bf16 v[56:59], v[184:187], v[208:211], v[56:59]
	v_mfma_f32_16x16x32_bf16 v[44:47], v[158:161], v[216:219], v[44:47]
	v_mfma_f32_16x16x32_bf16 v[40:43], v[184:187], v[216:219], v[40:43]
	v_mfma_f32_16x16x32_bf16 v[28:31], v[158:161], v[224:227], v[28:31]
	v_mfma_f32_16x16x32_bf16 v[24:27], v[184:187], v[224:227], v[24:27]
	v_mfma_f32_16x16x32_bf16 v[12:15], v[158:161], v[232:235], v[12:15]
	v_mfma_f32_16x16x32_bf16 v[8:11], v[184:187], v[232:235], v[8:11]
	v_mfma_f32_16x16x32_bf16 v[60:63], v[162:165], v[212:215], v[60:63]
	v_mfma_f32_16x16x32_bf16 v[56:59], v[188:191], v[212:215], v[56:59]
	v_mfma_f32_16x16x32_bf16 v[44:47], v[162:165], v[220:223], v[44:47]
	v_mfma_f32_16x16x32_bf16 v[40:43], v[188:191], v[220:223], v[40:43]
	v_mfma_f32_16x16x32_bf16 v[28:31], v[162:165], v[228:231], v[28:31]
	v_mfma_f32_16x16x32_bf16 v[24:27], v[188:191], v[228:231], v[24:27]
	v_mfma_f32_16x16x32_bf16 v[12:15], v[162:165], v[236:239], v[12:15]
	v_mfma_f32_16x16x32_bf16 v[8:11], v[188:191], v[236:239], v[8:11]
	s_setprio 0
	s_setprio 1
	v_mfma_f32_16x16x32_bf16 v[52:55], v[192:195], v[208:211], v[52:55]
	v_mfma_f32_16x16x32_bf16 v[48:51], v[200:203], v[208:211], v[48:51]
	v_mfma_f32_16x16x32_bf16 v[36:39], v[192:195], v[216:219], v[36:39]
	v_mfma_f32_16x16x32_bf16 v[32:35], v[200:203], v[216:219], v[32:35]
	v_mfma_f32_16x16x32_bf16 v[20:23], v[192:195], v[224:227], v[20:23]
	v_mfma_f32_16x16x32_bf16 v[16:19], v[200:203], v[224:227], v[16:19]
	v_mfma_f32_16x16x32_bf16 v[4:7], v[192:195], v[232:235], v[4:7]
	v_mfma_f32_16x16x32_bf16 v[0:3], v[200:203], v[232:235], v[0:3]
	v_mfma_f32_16x16x32_bf16 v[52:55], v[196:199], v[212:215], v[52:55]
	v_mfma_f32_16x16x32_bf16 v[48:51], v[204:207], v[212:215], v[48:51]
	v_mfma_f32_16x16x32_bf16 v[36:39], v[196:199], v[220:223], v[36:39]
	v_mfma_f32_16x16x32_bf16 v[32:35], v[204:207], v[220:223], v[32:35]
	v_mfma_f32_16x16x32_bf16 v[20:23], v[196:199], v[228:231], v[20:23]
	v_mfma_f32_16x16x32_bf16 v[16:19], v[204:207], v[228:231], v[16:19]
	s_setprio 2
	s_barrier
	v_mfma_f32_16x16x32_bf16 v[4:7], v[196:199], v[236:239], v[4:7]
	v_mfma_f32_16x16x32_bf16 v[0:3], v[204:207], v[236:239], v[0:3]
	s_setprio 0
	s_add_i32 s16, 0, 0x18000
	v_add_u32_e32 v128, s16, v149
	s_add_i32 s17, 0, 0x1c000
	ds_read_b128 v[158:161], v128
	ds_read_b128 v[162:165], v128 offset:1024
	ds_read_b128 v[184:187], v128 offset:2048
	ds_read_b128 v[188:191], v128 offset:3072
	v_add_u32_e32 v128, s17, v149
	ds_read_b128 v[192:195], v128
	ds_read_b128 v[196:199], v128 offset:1024
	ds_read_b128 v[200:203], v128 offset:2048
	ds_read_b128 v[204:207], v128 offset:3072
	s_add_u32 s14, s54, 0x40000
	s_addc_u32 s15, s55, 0
	s_mov_b32 m0, s61
	v_lshl_add_u64 v[242:243], s[14:15], 0, v[138:139]
	ds_read_b128 v[208:211], v147 offset:32768
	ds_read_b128 v[212:215], v147 offset:33792
	ds_read_b128 v[216:219], v147 offset:34816
	ds_read_b128 v[220:223], v147 offset:35840
	ds_read_b128 v[224:227], v147 offset:36864
	ds_read_b128 v[228:231], v147 offset:37888
	ds_read_b128 v[232:235], v147 offset:38912
	ds_read_b128 v[236:239], v147 offset:39936
	global_load_lds_dwordx4 v[242:243], off
	v_lshl_add_u64 v[242:243], s[14:15], 0, v[142:143]
	s_mov_b32 m0, s62
	s_nop 0
	global_load_lds_dwordx4 v[242:243], off
	s_waitcnt vmcnt(8)
	s_waitcnt lgkmcnt(0)
	s_setprio 1
	s_barrier
	v_mfma_f32_16x16x32_bf16 v[124:127], v[158:161], v[208:211], v[124:127]
	v_mfma_f32_16x16x32_bf16 v[120:123], v[184:187], v[208:211], v[120:123]
	v_mfma_f32_16x16x32_bf16 v[108:111], v[158:161], v[216:219], v[108:111]
	v_mfma_f32_16x16x32_bf16 v[104:107], v[184:187], v[216:219], v[104:107]
	v_mfma_f32_16x16x32_bf16 v[92:95], v[158:161], v[224:227], v[92:95]
	v_mfma_f32_16x16x32_bf16 v[88:91], v[184:187], v[224:227], v[88:91]
	v_mfma_f32_16x16x32_bf16 v[76:79], v[158:161], v[232:235], v[76:79]
	v_mfma_f32_16x16x32_bf16 v[72:75], v[184:187], v[232:235], v[72:75]
	v_mfma_f32_16x16x32_bf16 v[124:127], v[162:165], v[212:215], v[124:127]
	v_mfma_f32_16x16x32_bf16 v[120:123], v[188:191], v[212:215], v[120:123]
	v_mfma_f32_16x16x32_bf16 v[108:111], v[162:165], v[220:223], v[108:111]
	v_mfma_f32_16x16x32_bf16 v[104:107], v[188:191], v[220:223], v[104:107]
	v_mfma_f32_16x16x32_bf16 v[92:95], v[162:165], v[228:231], v[92:95]
	v_mfma_f32_16x16x32_bf16 v[88:91], v[188:191], v[228:231], v[88:91]
	v_mfma_f32_16x16x32_bf16 v[76:79], v[162:165], v[236:239], v[76:79]
	v_mfma_f32_16x16x32_bf16 v[72:75], v[188:191], v[236:239], v[72:75]
	s_setprio 0
	s_setprio 1
	v_mfma_f32_16x16x32_bf16 v[116:119], v[192:195], v[208:211], v[116:119]
	v_mfma_f32_16x16x32_bf16 v[112:115], v[200:203], v[208:211], v[112:115]
	v_mfma_f32_16x16x32_bf16 v[100:103], v[192:195], v[216:219], v[100:103]
	v_mfma_f32_16x16x32_bf16 v[96:99], v[200:203], v[216:219], v[96:99]
	v_mfma_f32_16x16x32_bf16 v[84:87], v[192:195], v[224:227], v[84:87]
	v_mfma_f32_16x16x32_bf16 v[80:83], v[200:203], v[224:227], v[80:83]
	v_mfma_f32_16x16x32_bf16 v[68:71], v[192:195], v[232:235], v[68:71]
	v_mfma_f32_16x16x32_bf16 v[64:67], v[200:203], v[232:235], v[64:67]
	v_mfma_f32_16x16x32_bf16 v[116:119], v[196:199], v[212:215], v[116:119]
	v_mfma_f32_16x16x32_bf16 v[112:115], v[204:207], v[212:215], v[112:115]
	v_mfma_f32_16x16x32_bf16 v[100:103], v[196:199], v[220:223], v[100:103]
	v_mfma_f32_16x16x32_bf16 v[96:99], v[204:207], v[220:223], v[96:99]
	v_mfma_f32_16x16x32_bf16 v[84:87], v[196:199], v[228:231], v[84:87]
	v_mfma_f32_16x16x32_bf16 v[80:83], v[204:207], v[228:231], v[80:83]
	s_setprio 2
	s_barrier
; #define PG8_STAGE(bufoff, gbase, voff) do { _Pragma("unroll") for (int _i = 0; _i < 2; ++_i) \
;         __builtin_amdgcn_global_load_lds((const unsigned*)((const char*)(gbase) + (voff)[_i]), (LAS unsigned*)(lds + (bufoff) + ldsw + _i * 8192), 16, 0, 0); } while (0)
; #define PG8_LDA(dst, b, h) do { _Pragma("unroll") for (int m = 0; m < 4; ++m) _Pragma("unroll") for (int k = 0; k < 2; ++k) dst[m][k] = *(const LAS bf16x8*)(lds + PG8_SA(b, h) + aoff + m * 2048 + k * 1024); } while (0)
; #define PG8_MMA(ai, bj, At, Bt) do { __builtin_amdgcn_s_setprio(1); _Pragma("unroll") for (int m = 0; m < 4; ++m) _Pragma("unroll") for (int n = 0; n < 2; ++n) _Pragma("unroll") for (int k = 0; k < 2; ++k) \
;         acc[ai][bj][m][n] = __builtin_amdgcn_mfma_f32_16x16x32_bf16(Bt[n][k], At[m][k], acc[ai][bj][m][n], 0, 0, 0); __builtin_amdgcn_s_setprio(0); } while (0)
; #define PG8_WAIT_V(n) asm volatile("s_waitcnt vmcnt(" #n ")" ::: "memory")
; #define PG8_WAIT_L(n) asm volatile("s_waitcnt lgkmcnt(" #n ")" ::: "memory")
; #define PG8_BAR __builtin_amdgcn_s_barrier()
; #define PG8_SCHED __builtin_amdgcn_sched_barrier(0)
; template <class Epi, class Sched>
; __device__ __forceinline__ void gemm_phase(LAS unsigned char* lds, const int K, const Sched& S, const Epi& E) {
;     ...
;             PG8_LDA(At, 1, 1); PG8_STAGE(PG8_SB(1, 0), b3, voffB); PG8_STAGE(PG8_SB(1, 1), b3 + hstep, voffB); PG8_STAGE(PG8_SA(1, 0), a3, voffA);
;             PG8_WAIT_V(8); PG8_WAIT_L(0); PG8_BAR; PG8_MMA(1, 0, At, B0); PG8_MMA(1, 1, At, B1); PG8_BAR; PG8_SCHED;
;         }
;         if (wr == 0) PG8_BAR;
	v_mfma_f32_16x16x32_bf16 v[68:71], v[196:199], v[236:239], v[68:71]
	v_mfma_f32_16x16x32_bf16 v[64:67], v[204:207], v[236:239], v[64:67]
	s_setprio 0
	s_add_i32 s14, s16, s58
	v_lshl_add_u64 v[166:167], v[166:167], 0, s[36:37]
	s_mov_b32 m0, s14
	ds_read_b128 v[208:211], v147 offset:49152
	ds_read_b128 v[212:215], v147 offset:50176
	ds_read_b128 v[216:219], v147 offset:51200
	ds_read_b128 v[220:223], v147 offset:52224
	ds_read_b128 v[224:227], v147 offset:53248
	ds_read_b128 v[228:231], v147 offset:54272
	ds_read_b128 v[232:235], v147 offset:55296
	ds_read_b128 v[236:239], v147 offset:56320
	global_load_lds_dwordx4 v[166:167], off
	s_add_i32 m0, s14, 0x2000
	s_add_u32 s14, s38, 0x40080
	v_lshl_add_u64 v[166:167], v[180:181], 0, s[36:37]
	s_addc_u32 s15, s39, 0
	s_add_i32 s16, s17, s58
	global_load_lds_dwordx4 v[166:167], off
	v_lshl_add_u64 v[166:167], s[14:15], 0, v[140:141]
	s_mov_b32 m0, s16
	s_nop 0
	global_load_lds_dwordx4 v[166:167], off
	v_lshl_add_u64 v[166:167], s[14:15], 0, v[144:145]
	s_add_i32 m0, s16, 0x2000
	s_nop 0
	global_load_lds_dwordx4 v[166:167], off
	v_lshl_add_u64 v[166:167], v[182:183], 0, s[36:37]
	s_mov_b32 m0, s64
	s_nop 0
	global_load_lds_dwordx4 v[166:167], off
	v_lshl_add_u64 v[166:167], v[240:241], 0, s[36:37]
	s_mov_b32 m0, s65
	s_nop 0
	global_load_lds_dwordx4 v[166:167], off
	s_waitcnt vmcnt(8)
	s_waitcnt lgkmcnt(0)
	s_setprio 1
	s_barrier
	v_mfma_f32_16x16x32_bf16 v[60:63], v[158:161], v[208:211], v[60:63]
	v_mfma_f32_16x16x32_bf16 v[56:59], v[184:187], v[208:211], v[56:59]
	v_mfma_f32_16x16x32_bf16 v[44:47], v[158:161], v[216:219], v[44:47]
	v_mfma_f32_16x16x32_bf16 v[40:43], v[184:187], v[216:219], v[40:43]
	v_mfma_f32_16x16x32_bf16 v[28:31], v[158:161], v[224:227], v[28:31]
	v_mfma_f32_16x16x32_bf16 v[24:27], v[184:187], v[224:227], v[24:27]
	v_mfma_f32_16x16x32_bf16 v[12:15], v[158:161], v[232:235], v[12:15]
	v_mfma_f32_16x16x32_bf16 v[8:11], v[184:187], v[232:235], v[8:11]
	v_mfma_f32_16x16x32_bf16 v[60:63], v[162:165], v[212:215], v[60:63]
	v_mfma_f32_16x16x32_bf16 v[56:59], v[188:191], v[212:215], v[56:59]
	v_mfma_f32_16x16x32_bf16 v[44:47], v[162:165], v[220:223], v[44:47]
	v_mfma_f32_16x16x32_bf16 v[40:43], v[188:191], v[220:223], v[40:43]
	v_mfma_f32_16x16x32_bf16 v[28:31], v[162:165], v[228:231], v[28:31]
	v_mfma_f32_16x16x32_bf16 v[24:27], v[188:191], v[228:231], v[24:27]
	v_mfma_f32_16x16x32_bf16 v[12:15], v[162:165], v[236:239], v[12:15]
	v_mfma_f32_16x16x32_bf16 v[8:11], v[188:191], v[236:239], v[8:11]
	s_setprio 0
	s_setprio 1
	v_mfma_f32_16x16x32_bf16 v[52:55], v[192:195], v[208:211], v[52:55]
	v_mfma_f32_16x16x32_bf16 v[48:51], v[200:203], v[208:211], v[48:51]
	v_mfma_f32_16x16x32_bf16 v[36:39], v[192:195], v[216:219], v[36:39]
	v_mfma_f32_16x16x32_bf16 v[32:35], v[200:203], v[216:219], v[32:35]
	v_mfma_f32_16x16x32_bf16 v[20:23], v[192:195], v[224:227], v[20:23]
	v_mfma_f32_16x16x32_bf16 v[16:19], v[200:203], v[224:227], v[16:19]
	v_mfma_f32_16x16x32_bf16 v[4:7], v[192:195], v[232:235], v[4:7]
	v_mfma_f32_16x16x32_bf16 v[0:3], v[200:203], v[232:235], v[0:3]
	v_mfma_f32_16x16x32_bf16 v[52:55], v[196:199], v[212:215], v[52:55]
	v_mfma_f32_16x16x32_bf16 v[48:51], v[204:207], v[212:215], v[48:51]
	v_mfma_f32_16x16x32_bf16 v[36:39], v[196:199], v[220:223], v[36:39]
	v_mfma_f32_16x16x32_bf16 v[32:35], v[204:207], v[220:223], v[32:35]
	v_mfma_f32_16x16x32_bf16 v[20:23], v[196:199], v[228:231], v[20:23]
	v_mfma_f32_16x16x32_bf16 v[16:19], v[204:207], v[228:231], v[16:19]
	s_setprio 2
	s_barrier
	v_mfma_f32_16x16x32_bf16 v[4:7], v[196:199], v[236:239], v[4:7]
	v_mfma_f32_16x16x32_bf16 v[0:3], v[204:207], v[236:239], v[0:3]
	s_setprio 0
	s_add_i32 s13, s13, 2
	s_add_u32 s8, s8, 0x100
	s_addc_u32 s9, s9, 0
	s_add_u32 s11, s11, 0x100
	s_addc_u32 s12, s12, 0
	s_cmp_gt_u32 s13, 13
	s_cbranch_scc0 .LBB0_403
	s_and_b64 vcc, exec, s[42:43]
	s_cbranch_vccz .LBB0_406
	s_barrier

; #define PG8_STAGE(bufoff, gbase, voff) do { _Pragma("unroll") for (int _i = 0; _i < 2; ++_i) \
;         __builtin_amdgcn_global_load_lds((const unsigned*)((const char*)(gbase) + (voff)[_i]), (LAS unsigned*)(lds + (bufoff) + ldsw + _i * 8192), 16, 0, 0); } while (0)
; #define PG8_LDA(dst, b, h) do { _Pragma("unroll") for (int m = 0; m < 4; ++m) _Pragma("unroll") for (int k = 0; k < 2; ++k) dst[m][k] = *(const LAS bf16x8*)(lds + PG8_SA(b, h) + aoff + m * 2048 + k * 1024); } while (0)
; #define PG8_LDB(dst, b, h) do { _Pragma("unroll") for (int n = 0; n < 2; ++n) _Pragma("unroll") for (int k = 0; k < 2; ++k) dst[n][k] = *(const LAS bf16x8*)(lds + PG8_SB(b, h) + boff + n * 2048 + k * 1024); } while (0)
; #define PG8_MMA(ai, bj, At, Bt) do { __builtin_amdgcn_s_setprio(1); _Pragma("unroll") for (int m = 0; m < 4; ++m) _Pragma("unroll") for (int n = 0; n < 2; ++n) _Pragma("unroll") for (int k = 0; k < 2; ++k) \
;         acc[ai][bj][m][n] = __builtin_amdgcn_mfma_f32_16x16x32_bf16(Bt[n][k], At[m][k], acc[ai][bj][m][n], 0, 0, 0); __builtin_amdgcn_s_setprio(0); } while (0)
; #define PG8_WAIT_V(n) asm volatile("s_waitcnt vmcnt(" #n ")" ::: "memory")
; #define PG8_WAIT_L(n) asm volatile("s_waitcnt lgkmcnt(" #n ")" ::: "memory")
; #define PG8_BAR __builtin_amdgcn_s_barrier()
; #define PG8_SCHED __builtin_amdgcn_sched_barrier(0)
; template <class Epi, class Sched>
; __device__ __forceinline__ void gemm_phase(LAS unsigned char* lds, const int K, const Sched& S, const Epi& E) {
;     ...
;             const bool last = (t == nt - 2);
;             const char* a1 = cA + (size_t)(t + 1) * kstep;
;             const char* a2 = last ? nA : cA + (size_t)(t + 2) * kstep; const char* b2 = last ? nB : cB + (size_t)(t + 2) * kstep;
;             const char* a3 = a2 + kstep; const char* b3 = b2 + kstep;
;             PG8_LDB(B0, 0, 0); PG8_LDB(B1, 0, 1); PG8_SCHED; PG8_LDA(At, 0, 0); PG8_STAGE(PG8_SA(1, 1), a1 + hstep, voffA);
;             PG8_WAIT_V(8); PG8_WAIT_L(0); PG8_BAR; PG8_MMA(0, 0, At, B0); PG8_MMA(0, 1, At, B1); PG8_BAR; PG8_SCHED;
;             PG8_LDA(At, 0, 1); PG8_STAGE(PG8_SB(0, 0), b2, voffB); PG8_STAGE(PG8_SB(0, 1), b2 + hstep, voffB); PG8_STAGE(PG8_SA(0, 0), a2, voffA);
;             PG8_WAIT_V(8); PG8_WAIT_L(0); PG8_BAR; PG8_MMA(1, 0, At, B0); PG8_MMA(1, 1, At, B1); PG8_BAR; PG8_SCHED;
.LBB0_511:
	s_add_i32 s14, s8, 0xfaf9e080
	s_cmp_lg_u32 s13, 60
	s_cselect_b32 s14, s14, 0
	s_add_u32 s40, s28, s14
	s_addc_u32 s41, s29, 0
	s_add_i32 s15, 0, 0x10000
	s_add_u32 s38, s34, s14
	s_addc_u32 s39, s35, 0
	s_add_i32 s16, 0, 0x14000
	v_add_u32_e32 v164, s15, v145
	v_add_u32_e32 v180, s16, v145
	ds_read_b128 v[152:155], v164
	ds_read_b128 v[156:159], v164 offset:1024
	ds_read_b128 v[160:163], v164 offset:2048
	ds_read_b128 v[164:167], v164 offset:3072
	ds_read_b128 v[184:187], v180
	ds_read_b128 v[188:191], v180 offset:1024
	ds_read_b128 v[192:195], v180 offset:2048
	ds_read_b128 v[196:199], v180 offset:3072
	v_lshl_add_u64 v[180:181], v[146:147], 0, s[8:9]
	s_add_i32 m0, s2, 0xc000
	ds_read_b128 v[200:203], v151
	ds_read_b128 v[204:207], v151 offset:1024
	ds_read_b128 v[208:211], v151 offset:2048
	ds_read_b128 v[212:215], v151 offset:3072
	ds_read_b128 v[216:219], v151 offset:4096
	ds_read_b128 v[220:223], v151 offset:5120
	ds_read_b128 v[224:227], v151 offset:6144
	ds_read_b128 v[228:231], v151 offset:7168
	global_load_lds_dwordx4 v[180:181], off
	v_lshl_add_u64 v[180:181], v[148:149], 0, s[8:9]
	s_add_i32 m0, s2, 0xe000
	s_nop 0
	global_load_lds_dwordx4 v[180:181], off
	s_waitcnt vmcnt(8)
	s_waitcnt lgkmcnt(0)
	s_setprio 1
	s_barrier
	v_mfma_f32_16x16x32_bf16 v[124:127], v[152:155], v[200:203], v[124:127]
	v_mfma_f32_16x16x32_bf16 v[120:123], v[160:163], v[200:203], v[120:123]
	v_mfma_f32_16x16x32_bf16 v[108:111], v[152:155], v[208:211], v[108:111]
	v_mfma_f32_16x16x32_bf16 v[104:107], v[160:163], v[208:211], v[104:107]
	v_mfma_f32_16x16x32_bf16 v[92:95], v[152:155], v[216:219], v[92:95]
	v_mfma_f32_16x16x32_bf16 v[88:91], v[160:163], v[216:219], v[88:91]
	v_mfma_f32_16x16x32_bf16 v[76:79], v[152:155], v[224:227], v[76:79]
	v_mfma_f32_16x16x32_bf16 v[72:75], v[160:163], v[224:227], v[72:75]
	v_mfma_f32_16x16x32_bf16 v[124:127], v[156:159], v[204:207], v[124:127]
	v_mfma_f32_16x16x32_bf16 v[120:123], v[164:167], v[204:207], v[120:123]
	v_mfma_f32_16x16x32_bf16 v[108:111], v[156:159], v[212:215], v[108:111]
	v_mfma_f32_16x16x32_bf16 v[104:107], v[164:167], v[212:215], v[104:107]
	v_mfma_f32_16x16x32_bf16 v[92:95], v[156:159], v[220:223], v[92:95]
	v_mfma_f32_16x16x32_bf16 v[88:91], v[164:167], v[220:223], v[88:91]
	v_mfma_f32_16x16x32_bf16 v[76:79], v[156:159], v[228:231], v[76:79]
	v_mfma_f32_16x16x32_bf16 v[72:75], v[164:167], v[228:231], v[72:75]
	s_setprio 0
	s_setprio 1
	v_mfma_f32_16x16x32_bf16 v[116:119], v[184:187], v[200:203], v[116:119]
	v_mfma_f32_16x16x32_bf16 v[112:115], v[192:195], v[200:203], v[112:115]
	v_mfma_f32_16x16x32_bf16 v[100:103], v[184:187], v[208:211], v[100:103]
	v_mfma_f32_16x16x32_bf16 v[96:99], v[192:195], v[208:211], v[96:99]
	v_mfma_f32_16x16x32_bf16 v[84:87], v[184:187], v[216:219], v[84:87]
	v_mfma_f32_16x16x32_bf16 v[80:83], v[192:195], v[216:219], v[80:83]
	v_mfma_f32_16x16x32_bf16 v[68:71], v[184:187], v[224:227], v[68:71]
	v_mfma_f32_16x16x32_bf16 v[64:67], v[192:195], v[224:227], v[64:67]
	v_mfma_f32_16x16x32_bf16 v[116:119], v[188:191], v[204:207], v[116:119]
	v_mfma_f32_16x16x32_bf16 v[112:115], v[196:199], v[204:207], v[112:115]
	v_mfma_f32_16x16x32_bf16 v[100:103], v[188:191], v[212:215], v[100:103]
	v_mfma_f32_16x16x32_bf16 v[96:99], v[196:199], v[212:215], v[96:99]
	v_mfma_f32_16x16x32_bf16 v[84:87], v[188:191], v[220:223], v[84:87]
	v_mfma_f32_16x16x32_bf16 v[80:83], v[196:199], v[220:223], v[80:83]
	s_setprio 2
	s_barrier
	v_mfma_f32_16x16x32_bf16 v[68:71], v[188:191], v[228:231], v[68:71]
	v_mfma_f32_16x16x32_bf16 v[64:67], v[196:199], v[228:231], v[64:67]
	s_setprio 0
	s_add_i32 s14, s15, s1
	v_lshl_add_u64 v[180:181], s[38:39], 0, v[128:129]
	s_mov_b32 m0, s14
	ds_read_b128 v[200:203], v151 offset:16384
	ds_read_b128 v[204:207], v151 offset:17408
	ds_read_b128 v[208:211], v151 offset:18432
	ds_read_b128 v[212:215], v151 offset:19456
	ds_read_b128 v[216:219], v151 offset:20480
	ds_read_b128 v[220:223], v151 offset:21504
	ds_read_b128 v[224:227], v151 offset:22528
	ds_read_b128 v[228:231], v151 offset:23552
	global_load_lds_dwordx4 v[180:181], off
	s_add_i32 m0, s14, 0x2000
	s_add_u32 s14, s38, 0x100000
	v_lshl_add_u64 v[182:183], s[38:39], 0, v[138:139]
	s_addc_u32 s15, s39, 0
	s_add_i32 s16, s16, s1
	global_load_lds_dwordx4 v[182:183], off
	v_lshl_add_u64 v[232:233], s[14:15], 0, v[128:129]
	s_mov_b32 m0, s16
	v_lshl_add_u64 v[234:235], s[40:41], 0, v[140:141]
	global_load_lds_dwordx4 v[232:233], off
	v_lshl_add_u64 v[232:233], s[14:15], 0, v[138:139]
	s_add_i32 m0, s16, 0x2000
	s_nop 0
	global_load_lds_dwordx4 v[232:233], off
	v_lshl_add_u64 v[232:233], s[40:41], 0, v[142:143]
	s_mov_b32 m0, s2
	s_nop 0
	global_load_lds_dwordx4 v[232:233], off
	s_mov_b32 m0, s3
	s_nop 0
	global_load_lds_dwordx4 v[234:235], off
	s_waitcnt vmcnt(8)
	s_waitcnt lgkmcnt(0)
	s_setprio 1
	s_barrier
; #define PG8_STAGE(bufoff, gbase, voff) do { _Pragma("unroll") for (int _i = 0; _i < 2; ++_i) \
;         __builtin_amdgcn_global_load_lds((const unsigned*)((const char*)(gbase) + (voff)[_i]), (LAS unsigned*)(lds + (bufoff) + ldsw + _i * 8192), 16, 0, 0); } while (0)
; #define PG8_LDA(dst, b, h) do { _Pragma("unroll") for (int m = 0; m < 4; ++m) _Pragma("unroll") for (int k = 0; k < 2; ++k) dst[m][k] = *(const LAS bf16x8*)(lds + PG8_SA(b, h) + aoff + m * 2048 + k * 1024); } while (0)
; #define PG8_LDB(dst, b, h) do { _Pragma("unroll") for (int n = 0; n < 2; ++n) _Pragma("unroll") for (int k = 0; k < 2; ++k) dst[n][k] = *(const LAS bf16x8*)(lds + PG8_SB(b, h) + boff + n * 2048 + k * 1024); } while (0)
; #define PG8_MMA(ai, bj, At, Bt) do { __builtin_amdgcn_s_setprio(1); _Pragma("unroll") for (int m = 0; m < 4; ++m) _Pragma("unroll") for (int n = 0; n < 2; ++n) _Pragma("unroll") for (int k = 0; k < 2; ++k) \
;         acc[ai][bj][m][n] = __builtin_amdgcn_mfma_f32_16x16x32_bf16(Bt[n][k], At[m][k], acc[ai][bj][m][n], 0, 0, 0); __builtin_amdgcn_s_setprio(0); } while (0)
; #define PG8_WAIT_V(n) asm volatile("s_waitcnt vmcnt(" #n ")" ::: "memory")
; #define PG8_WAIT_L(n) asm volatile("s_waitcnt lgkmcnt(" #n ")" ::: "memory")
; #define PG8_BAR __builtin_amdgcn_s_barrier()
; #define PG8_SCHED __builtin_amdgcn_sched_barrier(0)
; template <class Epi, class Sched>
; __device__ __forceinline__ void gemm_phase(LAS unsigned char* lds, const int K, const Sched& S, const Epi& E) {
;     ...
;             PG8_WAIT_V(8); PG8_WAIT_L(0); PG8_BAR; PG8_MMA(1, 0, At, B0); PG8_MMA(1, 1, At, B1); PG8_BAR; PG8_SCHED;
;             PG8_LDB(B0, 1, 0); PG8_LDB(B1, 1, 1); PG8_SCHED; PG8_LDA(At, 1, 0); PG8_STAGE(PG8_SA(0, 1), a2 + hstep, voffA);
;             PG8_WAIT_V(8); PG8_WAIT_L(0); PG8_BAR; PG8_MMA(0, 0, At, B0); PG8_MMA(0, 1, At, B1); PG8_BAR; PG8_SCHED;
;             PG8_LDA(At, 1, 1); PG8_STAGE(PG8_SB(1, 0), b3, voffB); PG8_STAGE(PG8_SB(1, 1), b3 + hstep, voffB); PG8_STAGE(PG8_SA(1, 0), a3, voffA);
;             PG8_WAIT_V(8); PG8_WAIT_L(0); PG8_BAR; PG8_MMA(1, 0, At, B0); PG8_MMA(1, 1, At, B1); PG8_BAR; PG8_SCHED;
	v_mfma_f32_16x16x32_bf16 v[60:63], v[152:155], v[200:203], v[60:63]
	v_mfma_f32_16x16x32_bf16 v[56:59], v[160:163], v[200:203], v[56:59]
	v_mfma_f32_16x16x32_bf16 v[44:47], v[152:155], v[208:211], v[44:47]
	v_mfma_f32_16x16x32_bf16 v[40:43], v[160:163], v[208:211], v[40:43]
	v_mfma_f32_16x16x32_bf16 v[28:31], v[152:155], v[216:219], v[28:31]
	v_mfma_f32_16x16x32_bf16 v[24:27], v[160:163], v[216:219], v[24:27]
	v_mfma_f32_16x16x32_bf16 v[12:15], v[152:155], v[224:227], v[12:15]
	v_mfma_f32_16x16x32_bf16 v[8:11], v[160:163], v[224:227], v[8:11]
	v_mfma_f32_16x16x32_bf16 v[60:63], v[156:159], v[204:207], v[60:63]
	v_mfma_f32_16x16x32_bf16 v[56:59], v[164:167], v[204:207], v[56:59]
	v_mfma_f32_16x16x32_bf16 v[44:47], v[156:159], v[212:215], v[44:47]
	v_mfma_f32_16x16x32_bf16 v[40:43], v[164:167], v[212:215], v[40:43]
	v_mfma_f32_16x16x32_bf16 v[28:31], v[156:159], v[220:223], v[28:31]
	v_mfma_f32_16x16x32_bf16 v[24:27], v[164:167], v[220:223], v[24:27]
	v_mfma_f32_16x16x32_bf16 v[12:15], v[156:159], v[228:231], v[12:15]
	v_mfma_f32_16x16x32_bf16 v[8:11], v[164:167], v[228:231], v[8:11]
	s_setprio 0
	s_setprio 1
	v_mfma_f32_16x16x32_bf16 v[52:55], v[184:187], v[200:203], v[52:55]
	v_mfma_f32_16x16x32_bf16 v[48:51], v[192:195], v[200:203], v[48:51]
	v_mfma_f32_16x16x32_bf16 v[36:39], v[184:187], v[208:211], v[36:39]
	v_mfma_f32_16x16x32_bf16 v[32:35], v[192:195], v[208:211], v[32:35]
	v_mfma_f32_16x16x32_bf16 v[20:23], v[184:187], v[216:219], v[20:23]
	v_mfma_f32_16x16x32_bf16 v[16:19], v[192:195], v[216:219], v[16:19]
	v_mfma_f32_16x16x32_bf16 v[4:7], v[184:187], v[224:227], v[4:7]
	v_mfma_f32_16x16x32_bf16 v[0:3], v[192:195], v[224:227], v[0:3]
	v_mfma_f32_16x16x32_bf16 v[52:55], v[188:191], v[204:207], v[52:55]
	v_mfma_f32_16x16x32_bf16 v[48:51], v[196:199], v[204:207], v[48:51]
	v_mfma_f32_16x16x32_bf16 v[36:39], v[188:191], v[212:215], v[36:39]
	v_mfma_f32_16x16x32_bf16 v[32:35], v[196:199], v[212:215], v[32:35]
	v_mfma_f32_16x16x32_bf16 v[20:23], v[188:191], v[220:223], v[20:23]
	v_mfma_f32_16x16x32_bf16 v[16:19], v[196:199], v[220:223], v[16:19]
	s_setprio 2
	s_barrier
	v_mfma_f32_16x16x32_bf16 v[4:7], v[188:191], v[228:231], v[4:7]
	v_mfma_f32_16x16x32_bf16 v[0:3], v[196:199], v[228:231], v[0:3]
	s_setprio 0
	s_add_i32 s16, 0, 0x18000
	s_add_i32 s17, 0, 0x1c000
	v_add_u32_e32 v164, s16, v145
	v_add_u32_e32 v196, s17, v145
	ds_read_b128 v[152:155], v164
	ds_read_b128 v[156:159], v164 offset:1024
	ds_read_b128 v[160:163], v164 offset:2048
	ds_read_b128 v[164:167], v164 offset:3072
	ds_read_b128 v[184:187], v196
	ds_read_b128 v[188:191], v196 offset:1024
	ds_read_b128 v[192:195], v196 offset:2048
	ds_read_b128 v[196:199], v196 offset:3072
	s_add_u32 s14, s40, 0x100000
	s_addc_u32 s15, s41, 0
	s_mov_b32 m0, s4
	v_lshl_add_u64 v[236:237], s[14:15], 0, v[142:143]
	ds_read_b128 v[200:203], v151 offset:32768
	ds_read_b128 v[204:207], v151 offset:33792
	ds_read_b128 v[208:211], v151 offset:34816
	ds_read_b128 v[212:215], v151 offset:35840
	ds_read_b128 v[216:219], v151 offset:36864
	ds_read_b128 v[220:223], v151 offset:37888
	ds_read_b128 v[224:227], v151 offset:38912
	ds_read_b128 v[228:231], v151 offset:39936
	global_load_lds_dwordx4 v[236:237], off
	v_lshl_add_u64 v[236:237], s[14:15], 0, v[140:141]
	s_mov_b32 m0, s5
	s_nop 0
	global_load_lds_dwordx4 v[236:237], off
	s_waitcnt vmcnt(8)
	s_waitcnt lgkmcnt(0)
	s_setprio 1
	s_barrier
	v_mfma_f32_16x16x32_bf16 v[124:127], v[152:155], v[200:203], v[124:127]
	v_mfma_f32_16x16x32_bf16 v[120:123], v[160:163], v[200:203], v[120:123]
	v_mfma_f32_16x16x32_bf16 v[108:111], v[152:155], v[208:211], v[108:111]
	v_mfma_f32_16x16x32_bf16 v[104:107], v[160:163], v[208:211], v[104:107]
	v_mfma_f32_16x16x32_bf16 v[92:95], v[152:155], v[216:219], v[92:95]
	v_mfma_f32_16x16x32_bf16 v[88:91], v[160:163], v[216:219], v[88:91]
	v_mfma_f32_16x16x32_bf16 v[76:79], v[152:155], v[224:227], v[76:79]
	v_mfma_f32_16x16x32_bf16 v[72:75], v[160:163], v[224:227], v[72:75]
	v_mfma_f32_16x16x32_bf16 v[124:127], v[156:159], v[204:207], v[124:127]
	v_mfma_f32_16x16x32_bf16 v[120:123], v[164:167], v[204:207], v[120:123]
	v_mfma_f32_16x16x32_bf16 v[108:111], v[156:159], v[212:215], v[108:111]
	v_mfma_f32_16x16x32_bf16 v[104:107], v[164:167], v[212:215], v[104:107]
	v_mfma_f32_16x16x32_bf16 v[92:95], v[156:159], v[220:223], v[92:95]
	v_mfma_f32_16x16x32_bf16 v[88:91], v[164:167], v[220:223], v[88:91]
	v_mfma_f32_16x16x32_bf16 v[76:79], v[156:159], v[228:231], v[76:79]
	v_mfma_f32_16x16x32_bf16 v[72:75], v[164:167], v[228:231], v[72:75]
	s_setprio 0
	s_setprio 1
	v_mfma_f32_16x16x32_bf16 v[116:119], v[184:187], v[200:203], v[116:119]
	v_mfma_f32_16x16x32_bf16 v[112:115], v[192:195], v[200:203], v[112:115]
	v_mfma_f32_16x16x32_bf16 v[100:103], v[184:187], v[208:211], v[100:103]
	v_mfma_f32_16x16x32_bf16 v[96:99], v[192:195], v[208:211], v[96:99]
	v_mfma_f32_16x16x32_bf16 v[84:87], v[184:187], v[216:219], v[84:87]
	v_mfma_f32_16x16x32_bf16 v[80:83], v[192:195], v[216:219], v[80:83]
	v_mfma_f32_16x16x32_bf16 v[68:71], v[184:187], v[224:227], v[68:71]
	v_mfma_f32_16x16x32_bf16 v[64:67], v[192:195], v[224:227], v[64:67]
	v_mfma_f32_16x16x32_bf16 v[116:119], v[188:191], v[204:207], v[116:119]
	v_mfma_f32_16x16x32_bf16 v[112:115], v[196:199], v[204:207], v[112:115]
	v_mfma_f32_16x16x32_bf16 v[100:103], v[188:191], v[212:215], v[100:103]
	v_mfma_f32_16x16x32_bf16 v[96:99], v[196:199], v[212:215], v[96:99]
	v_mfma_f32_16x16x32_bf16 v[84:87], v[188:191], v[220:223], v[84:87]
	v_mfma_f32_16x16x32_bf16 v[80:83], v[196:199], v[220:223], v[80:83]
	s_setprio 2
	s_barrier
; #define PG8_STAGE(bufoff, gbase, voff) do { _Pragma("unroll") for (int _i = 0; _i < 2; ++_i) \
;         __builtin_amdgcn_global_load_lds((const unsigned*)((const char*)(gbase) + (voff)[_i]), (LAS unsigned*)(lds + (bufoff) + ldsw + _i * 8192), 16, 0, 0); } while (0)
; #define PG8_LDA(dst, b, h) do { _Pragma("unroll") for (int m = 0; m < 4; ++m) _Pragma("unroll") for (int k = 0; k < 2; ++k) dst[m][k] = *(const LAS bf16x8*)(lds + PG8_SA(b, h) + aoff + m * 2048 + k * 1024); } while (0)
; #define PG8_MMA(ai, bj, At, Bt) do { __builtin_amdgcn_s_setprio(1); _Pragma("unroll") for (int m = 0; m < 4; ++m) _Pragma("unroll") for (int n = 0; n < 2; ++n) _Pragma("unroll") for (int k = 0; k < 2; ++k) \
;         acc[ai][bj][m][n] = __builtin_amdgcn_mfma_f32_16x16x32_bf16(Bt[n][k], At[m][k], acc[ai][bj][m][n], 0, 0, 0); __builtin_amdgcn_s_setprio(0); } while (0)
; #define PG8_WAIT_V(n) asm volatile("s_waitcnt vmcnt(" #n ")" ::: "memory")
; #define PG8_WAIT_L(n) asm volatile("s_waitcnt lgkmcnt(" #n ")" ::: "memory")
; #define PG8_BAR __builtin_amdgcn_s_barrier()
; #define PG8_SCHED __builtin_amdgcn_sched_barrier(0)
; template <class Epi, class Sched>
; __device__ __forceinline__ void gemm_phase(LAS unsigned char* lds, const int K, const Sched& S, const Epi& E) {
;     ...
;             PG8_LDA(At, 1, 1); PG8_STAGE(PG8_SB(1, 0), b3, voffB); PG8_STAGE(PG8_SB(1, 1), b3 + hstep, voffB); PG8_STAGE(PG8_SA(1, 0), a3, voffA);
;             PG8_WAIT_V(8); PG8_WAIT_L(0); PG8_BAR; PG8_MMA(1, 0, At, B0); PG8_MMA(1, 1, At, B1); PG8_BAR; PG8_SCHED;
;         }
;         if (wr == 0) PG8_BAR;
	v_mfma_f32_16x16x32_bf16 v[68:71], v[188:191], v[228:231], v[68:71]
	v_mfma_f32_16x16x32_bf16 v[64:67], v[196:199], v[228:231], v[64:67]
	s_setprio 0
	s_add_i32 s14, s16, s1
	v_lshl_add_u64 v[180:181], v[180:181], 0, s[36:37]
	s_mov_b32 m0, s14
	ds_read_b128 v[200:203], v151 offset:49152
	ds_read_b128 v[204:207], v151 offset:50176
	ds_read_b128 v[208:211], v151 offset:51200
	ds_read_b128 v[212:215], v151 offset:52224
	ds_read_b128 v[216:219], v151 offset:53248
	ds_read_b128 v[220:223], v151 offset:54272
	ds_read_b128 v[224:227], v151 offset:55296
	ds_read_b128 v[228:231], v151 offset:56320
	global_load_lds_dwordx4 v[180:181], off
	s_add_i32 m0, s14, 0x2000
	s_add_u32 s14, s38, 0x100080
	v_lshl_add_u64 v[180:181], v[182:183], 0, s[36:37]
	s_addc_u32 s15, s39, 0
	s_add_i32 s16, s17, s1
	global_load_lds_dwordx4 v[180:181], off
	v_lshl_add_u64 v[180:181], s[14:15], 0, v[128:129]
	s_mov_b32 m0, s16
	s_nop 0
	global_load_lds_dwordx4 v[180:181], off
	v_lshl_add_u64 v[180:181], s[14:15], 0, v[138:139]
	s_add_i32 m0, s16, 0x2000
	s_nop 0
	global_load_lds_dwordx4 v[180:181], off
	v_lshl_add_u64 v[180:181], v[232:233], 0, s[36:37]
	s_mov_b32 m0, s11
	s_nop 0
	global_load_lds_dwordx4 v[180:181], off
	v_lshl_add_u64 v[180:181], v[234:235], 0, s[36:37]
	s_mov_b32 m0, s12
	s_nop 0
	global_load_lds_dwordx4 v[180:181], off
	s_waitcnt vmcnt(8)
	s_waitcnt lgkmcnt(0)
	s_setprio 1
	s_barrier
	v_mfma_f32_16x16x32_bf16 v[60:63], v[152:155], v[200:203], v[60:63]
	v_mfma_f32_16x16x32_bf16 v[56:59], v[160:163], v[200:203], v[56:59]
	v_mfma_f32_16x16x32_bf16 v[44:47], v[152:155], v[208:211], v[44:47]
	v_mfma_f32_16x16x32_bf16 v[40:43], v[160:163], v[208:211], v[40:43]
	v_mfma_f32_16x16x32_bf16 v[28:31], v[152:155], v[216:219], v[28:31]
	v_mfma_f32_16x16x32_bf16 v[24:27], v[160:163], v[216:219], v[24:27]
	v_mfma_f32_16x16x32_bf16 v[12:15], v[152:155], v[224:227], v[12:15]
	v_mfma_f32_16x16x32_bf16 v[8:11], v[160:163], v[224:227], v[8:11]
	v_mfma_f32_16x16x32_bf16 v[60:63], v[156:159], v[204:207], v[60:63]
	v_mfma_f32_16x16x32_bf16 v[56:59], v[164:167], v[204:207], v[56:59]
	v_mfma_f32_16x16x32_bf16 v[44:47], v[156:159], v[212:215], v[44:47]
	v_mfma_f32_16x16x32_bf16 v[40:43], v[164:167], v[212:215], v[40:43]
	v_mfma_f32_16x16x32_bf16 v[28:31], v[156:159], v[220:223], v[28:31]
	v_mfma_f32_16x16x32_bf16 v[24:27], v[164:167], v[220:223], v[24:27]
	v_mfma_f32_16x16x32_bf16 v[12:15], v[156:159], v[228:231], v[12:15]
	v_mfma_f32_16x16x32_bf16 v[8:11], v[164:167], v[228:231], v[8:11]
	s_setprio 0
	s_setprio 1
	v_mfma_f32_16x16x32_bf16 v[52:55], v[184:187], v[200:203], v[52:55]
	v_mfma_f32_16x16x32_bf16 v[48:51], v[192:195], v[200:203], v[48:51]
	v_mfma_f32_16x16x32_bf16 v[36:39], v[184:187], v[208:211], v[36:39]
	v_mfma_f32_16x16x32_bf16 v[32:35], v[192:195], v[208:211], v[32:35]
	v_mfma_f32_16x16x32_bf16 v[20:23], v[184:187], v[216:219], v[20:23]
	v_mfma_f32_16x16x32_bf16 v[16:19], v[192:195], v[216:219], v[16:19]
	v_mfma_f32_16x16x32_bf16 v[4:7], v[184:187], v[224:227], v[4:7]
	v_mfma_f32_16x16x32_bf16 v[0:3], v[192:195], v[224:227], v[0:3]
	v_mfma_f32_16x16x32_bf16 v[52:55], v[188:191], v[204:207], v[52:55]
	v_mfma_f32_16x16x32_bf16 v[48:51], v[196:199], v[204:207], v[48:51]
	v_mfma_f32_16x16x32_bf16 v[36:39], v[188:191], v[212:215], v[36:39]
	v_mfma_f32_16x16x32_bf16 v[32:35], v[196:199], v[212:215], v[32:35]
	v_mfma_f32_16x16x32_bf16 v[20:23], v[188:191], v[220:223], v[20:23]
	v_mfma_f32_16x16x32_bf16 v[16:19], v[196:199], v[220:223], v[16:19]
	s_setprio 2
	s_barrier
	v_mfma_f32_16x16x32_bf16 v[4:7], v[188:191], v[228:231], v[4:7]
	v_mfma_f32_16x16x32_bf16 v[0:3], v[196:199], v[228:231], v[0:3]
	s_setprio 0
	s_add_i32 s13, s13, 2
	s_add_u32 s8, s8, 0x100
	s_addc_u32 s9, s9, 0
	s_cmp_gt_u32 s13, 61
	s_cbranch_scc0 .LBB0_511
	s_cmpk_lt_u32 s0, 0x100
	s_cbranch_scc0 .LBB0_514
	s_barrier

; #define PG8_STAGE(bufoff, gbase, voff) do { _Pragma("unroll") for (int _i = 0; _i < 2; ++_i) \
;         __builtin_amdgcn_global_load_lds((const unsigned*)((const char*)(gbase) + (voff)[_i]), (LAS unsigned*)(lds + (bufoff) + ldsw + _i * 8192), 16, 0, 0); } while (0)
; #define PG8_LDA(dst, b, h) do { _Pragma("unroll") for (int m = 0; m < 4; ++m) _Pragma("unroll") for (int k = 0; k < 2; ++k) dst[m][k] = *(const LAS bf16x8*)(lds + PG8_SA(b, h) + aoff + m * 2048 + k * 1024); } while (0)
; #define PG8_LDB(dst, b, h) do { _Pragma("unroll") for (int n = 0; n < 2; ++n) _Pragma("unroll") for (int k = 0; k < 2; ++k) dst[n][k] = *(const LAS bf16x8*)(lds + PG8_SB(b, h) + boff + n * 2048 + k * 1024); } while (0)
; #define PG8_MMA(ai, bj, At, Bt) do { __builtin_amdgcn_s_setprio(1); _Pragma("unroll") for (int m = 0; m < 4; ++m) _Pragma("unroll") for (int n = 0; n < 2; ++n) _Pragma("unroll") for (int k = 0; k < 2; ++k) \
;         acc[ai][bj][m][n] = __builtin_amdgcn_mfma_f32_16x16x32_bf16(Bt[n][k], At[m][k], acc[ai][bj][m][n], 0, 0, 0); __builtin_amdgcn_s_setprio(0); } while (0)
; #define PG8_WAIT_V(n) asm volatile("s_waitcnt vmcnt(" #n ")" ::: "memory")
; template <class Epi, class Sched>
; __device__ __forceinline__ void gemm_phase(LAS unsigned char* lds, const int K, const Sched& S, const Epi& E) {
;     ...
;         const bool has_next = S.next(ui + 1, nxt);
;         const char* nA = has_next ? nxt.a : cA; const char* nB = has_next ? nxt.b : cB;
;         const int nt = cur.pad;
; #pragma unroll 1
;         for (int t = 0; t < nt; t += 2) {
;             const bool last = (t == nt - 2);
;             const char* a1 = cA + (size_t)(t + 1) * kstep;
;             const char* a2 = last ? nA : cA + (size_t)(t + 2) * kstep; const char* b2 = last ? nB : cB + (size_t)(t + 2) * kstep;
;             const char* a3 = a2 + kstep; const char* b3 = b2 + kstep;
;             PG8_LDB(B0, 0, 0); PG8_LDB(B1, 0, 1); PG8_SCHED; PG8_LDA(At, 0, 0); PG8_STAGE(PG8_SA(1, 1), a1 + hstep, voffA);
;             PG8_WAIT_V(8); PG8_WAIT_L(0); PG8_BAR; PG8_MMA(0, 0, At, B0); PG8_MMA(0, 1, At, B1); PG8_BAR; PG8_SCHED;
;             PG8_LDA(At, 0, 1); PG8_STAGE(PG8_SB(0, 0), b2, voffB); PG8_STAGE(PG8_SB(0, 1), b2 + hstep, voffB); PG8_STAGE(PG8_SA(0, 0), a2, voffA);
;             PG8_WAIT_V(8); PG8_WAIT_L(0); PG8_BAR; PG8_MMA(1, 0, At, B0); PG8_MMA(1, 1, At, B1); PG8_BAR; PG8_SCHED;
.LBB0_533:
	s_add_u32 s14, s50, s11
	s_addc_u32 s15, s51, 0
	s_add_u32 s16, s14, 0x100
	s_addc_u32 s17, s15, 0
	s_and_b64 s[12:13], s[54:55], exec
	s_cselect_b32 s59, s45, s17
	s_cselect_b32 s58, s44, s16
	s_add_u32 s11, s8, s11
	s_addc_u32 s12, s9, 0
	s_add_u32 s11, s11, 0x100
	s_addc_u32 s16, s12, 0
	s_add_i32 s21, 0, 0x10000
	s_and_b64 s[12:13], s[54:55], exec
	s_cselect_b32 s61, s47, s16
	s_cselect_b32 s60, s46, s11
	s_add_i32 s25, 0, 0x14000
	s_add_u32 s64, s14, 0x10080
	s_addc_u32 s65, s15, 0
	s_add_i32 s19, s21, s3
	s_add_i32 m0, s26, 0xc000
	s_add_i32 s28, s26, 0xe000
	s_add_i32 s15, s19, 0x2000
	v_add_u32_e32 v146, s21, v148
	s_add_u32 s62, s60, 0x10000
	ds_read_b128 v[152:155], v146
	ds_read_b128 v[156:159], v146 offset:1024
	ds_read_b128 v[160:163], v146 offset:2048
	ds_read_b128 v[164:167], v146 offset:3072
	v_add_u32_e32 v146, s25, v148
	s_addc_u32 s63, s61, 0
	s_add_i32 s17, s25, s3
	ds_read_b128 v[184:187], v146
	ds_read_b128 v[188:191], v146 offset:1024
	ds_read_b128 v[192:195], v146 offset:2048
	ds_read_b128 v[196:199], v146 offset:3072
	s_add_i32 s16, s17, 0x2000
	s_add_i32 s14, 0, 0x18000
	s_add_i32 s13, 0, 0x1c000
	s_add_u32 s56, s58, 0x10000
	s_addc_u32 s57, s59, 0
	s_add_i32 s12, s14, s3
	s_add_i32 s11, s12, 0x2000
	s_add_u32 s54, s60, 0x10080
	s_addc_u32 s55, s61, 0
	s_add_i32 s25, s13, s3
	s_add_i32 s21, s25, 0x2000
	v_lshl_add_u64 v[146:147], s[64:65], 0, v[144:145]
	ds_read_b128 v[200:203], v150
	ds_read_b128 v[204:207], v150 offset:1024
	ds_read_b128 v[208:211], v150 offset:2048
	ds_read_b128 v[212:215], v150 offset:3072
	ds_read_b128 v[216:219], v150 offset:4096
	ds_read_b128 v[220:223], v150 offset:5120
	ds_read_b128 v[224:227], v150 offset:6144
	ds_read_b128 v[228:231], v150 offset:7168
	global_load_lds_dwordx4 v[146:147], off
	v_lshl_add_u64 v[146:147], s[64:65], 0, v[140:141]
	s_mov_b32 m0, s28
	s_nop 0
	global_load_lds_dwordx4 v[146:147], off
	s_waitcnt vmcnt(8)
	s_waitcnt lgkmcnt(0)
	s_setprio 1
	s_barrier
	v_mfma_f32_16x16x32_bf16 v[124:127], v[152:155], v[200:203], v[124:127]
	v_mfma_f32_16x16x32_bf16 v[120:123], v[160:163], v[200:203], v[120:123]
	v_mfma_f32_16x16x32_bf16 v[112:115], v[152:155], v[208:211], v[112:115]
	v_mfma_f32_16x16x32_bf16 v[104:107], v[160:163], v[208:211], v[104:107]
	v_mfma_f32_16x16x32_bf16 v[96:99], v[152:155], v[216:219], v[96:99]
	v_mfma_f32_16x16x32_bf16 v[88:91], v[160:163], v[216:219], v[88:91]
	v_mfma_f32_16x16x32_bf16 v[80:83], v[152:155], v[224:227], v[80:83]
	v_mfma_f32_16x16x32_bf16 v[72:75], v[160:163], v[224:227], v[72:75]
	v_mfma_f32_16x16x32_bf16 v[124:127], v[156:159], v[204:207], v[124:127]
	v_mfma_f32_16x16x32_bf16 v[120:123], v[164:167], v[204:207], v[120:123]
	v_mfma_f32_16x16x32_bf16 v[112:115], v[156:159], v[212:215], v[112:115]
	v_mfma_f32_16x16x32_bf16 v[104:107], v[164:167], v[212:215], v[104:107]
	v_mfma_f32_16x16x32_bf16 v[96:99], v[156:159], v[220:223], v[96:99]
	v_mfma_f32_16x16x32_bf16 v[88:91], v[164:167], v[220:223], v[88:91]
	v_mfma_f32_16x16x32_bf16 v[80:83], v[156:159], v[228:231], v[80:83]
	v_mfma_f32_16x16x32_bf16 v[72:75], v[164:167], v[228:231], v[72:75]
	s_setprio 0
	s_setprio 1
	v_mfma_f32_16x16x32_bf16 v[116:119], v[184:187], v[200:203], v[116:119]
	v_mfma_f32_16x16x32_bf16 v[108:111], v[192:195], v[200:203], v[108:111]
	v_mfma_f32_16x16x32_bf16 v[100:103], v[184:187], v[208:211], v[100:103]
	v_mfma_f32_16x16x32_bf16 v[92:95], v[192:195], v[208:211], v[92:95]
	v_mfma_f32_16x16x32_bf16 v[84:87], v[184:187], v[216:219], v[84:87]
	v_mfma_f32_16x16x32_bf16 v[76:79], v[192:195], v[216:219], v[76:79]
	v_mfma_f32_16x16x32_bf16 v[68:71], v[184:187], v[224:227], v[68:71]
	v_mfma_f32_16x16x32_bf16 v[64:67], v[192:195], v[224:227], v[64:67]
	v_mfma_f32_16x16x32_bf16 v[116:119], v[188:191], v[204:207], v[116:119]
	v_mfma_f32_16x16x32_bf16 v[108:111], v[196:199], v[204:207], v[108:111]
	v_mfma_f32_16x16x32_bf16 v[100:103], v[188:191], v[212:215], v[100:103]
	v_mfma_f32_16x16x32_bf16 v[92:95], v[196:199], v[212:215], v[92:95]
	v_mfma_f32_16x16x32_bf16 v[84:87], v[188:191], v[220:223], v[84:87]
	v_mfma_f32_16x16x32_bf16 v[76:79], v[196:199], v[220:223], v[76:79]
	s_setprio 2
	s_barrier
	v_mfma_f32_16x16x32_bf16 v[68:71], v[188:191], v[228:231], v[68:71]
	v_mfma_f32_16x16x32_bf16 v[64:67], v[196:199], v[228:231], v[64:67]
	s_setprio 0
	s_mov_b32 m0, s19
	v_lshl_add_u64 v[146:147], s[60:61], 0, v[142:143]
	ds_read_b128 v[200:203], v150 offset:16384
	ds_read_b128 v[204:207], v150 offset:17408
	ds_read_b128 v[208:211], v150 offset:18432
	ds_read_b128 v[212:215], v150 offset:19456
	ds_read_b128 v[216:219], v150 offset:20480
	ds_read_b128 v[220:223], v150 offset:21504
	ds_read_b128 v[224:227], v150 offset:22528
	ds_read_b128 v[228:231], v150 offset:23552
	global_load_lds_dwordx4 v[146:147], off
	v_lshl_add_u64 v[180:181], s[60:61], 0, v[138:139]
	s_mov_b32 m0, s15
	v_lshl_add_u64 v[182:183], s[62:63], 0, v[142:143]
	global_load_lds_dwordx4 v[180:181], off
	s_mov_b32 m0, s17
	v_lshl_add_u64 v[232:233], s[58:59], 0, v[140:141]
	global_load_lds_dwordx4 v[182:183], off
	v_lshl_add_u64 v[182:183], s[62:63], 0, v[138:139]
	s_mov_b32 m0, s16
	s_nop 0
	global_load_lds_dwordx4 v[182:183], off
	v_lshl_add_u64 v[182:183], s[58:59], 0, v[144:145]
	s_mov_b32 m0, s26
	s_nop 0
	global_load_lds_dwordx4 v[182:183], off
	s_mov_b32 m0, s27
	s_nop 0
	global_load_lds_dwordx4 v[232:233], off
	s_waitcnt vmcnt(8)
	s_waitcnt lgkmcnt(0)
	s_setprio 1
	s_barrier
; #define PG8_STAGE(bufoff, gbase, voff) do { _Pragma("unroll") for (int _i = 0; _i < 2; ++_i) \
;         __builtin_amdgcn_global_load_lds((const unsigned*)((const char*)(gbase) + (voff)[_i]), (LAS unsigned*)(lds + (bufoff) + ldsw + _i * 8192), 16, 0, 0); } while (0)
; #define PG8_LDA(dst, b, h) do { _Pragma("unroll") for (int m = 0; m < 4; ++m) _Pragma("unroll") for (int k = 0; k < 2; ++k) dst[m][k] = *(const LAS bf16x8*)(lds + PG8_SA(b, h) + aoff + m * 2048 + k * 1024); } while (0)
; #define PG8_LDB(dst, b, h) do { _Pragma("unroll") for (int n = 0; n < 2; ++n) _Pragma("unroll") for (int k = 0; k < 2; ++k) dst[n][k] = *(const LAS bf16x8*)(lds + PG8_SB(b, h) + boff + n * 2048 + k * 1024); } while (0)
; #define PG8_MMA(ai, bj, At, Bt) do { __builtin_amdgcn_s_setprio(1); _Pragma("unroll") for (int m = 0; m < 4; ++m) _Pragma("unroll") for (int n = 0; n < 2; ++n) _Pragma("unroll") for (int k = 0; k < 2; ++k) \
;         acc[ai][bj][m][n] = __builtin_amdgcn_mfma_f32_16x16x32_bf16(Bt[n][k], At[m][k], acc[ai][bj][m][n], 0, 0, 0); __builtin_amdgcn_s_setprio(0); } while (0)
; #define PG8_WAIT_V(n) asm volatile("s_waitcnt vmcnt(" #n ")" ::: "memory")
; #define PG8_WAIT_L(n) asm volatile("s_waitcnt lgkmcnt(" #n ")" ::: "memory")
; #define PG8_BAR __builtin_amdgcn_s_barrier()
; #define PG8_SCHED __builtin_amdgcn_sched_barrier(0)
; template <class Epi, class Sched>
; __device__ __forceinline__ void gemm_phase(LAS unsigned char* lds, const int K, const Sched& S, const Epi& E) {
;     ...
;             PG8_WAIT_V(8); PG8_WAIT_L(0); PG8_BAR; PG8_MMA(1, 0, At, B0); PG8_MMA(1, 1, At, B1); PG8_BAR; PG8_SCHED;
;             PG8_LDB(B0, 1, 0); PG8_LDB(B1, 1, 1); PG8_SCHED; PG8_LDA(At, 1, 0); PG8_STAGE(PG8_SA(0, 1), a2 + hstep, voffA);
;             PG8_WAIT_V(8); PG8_WAIT_L(0); PG8_BAR; PG8_MMA(0, 0, At, B0); PG8_MMA(0, 1, At, B1); PG8_BAR; PG8_SCHED;
;             PG8_LDA(At, 1, 1); PG8_STAGE(PG8_SB(1, 0), b3, voffB); PG8_STAGE(PG8_SB(1, 1), b3 + hstep, voffB); PG8_STAGE(PG8_SA(1, 0), a3, voffA);
;             PG8_WAIT_V(8); PG8_WAIT_L(0); PG8_BAR; PG8_MMA(1, 0, At, B0); PG8_MMA(1, 1, At, B1); PG8_BAR; PG8_SCHED;
	v_mfma_f32_16x16x32_bf16 v[60:63], v[152:155], v[200:203], v[60:63]
	v_mfma_f32_16x16x32_bf16 v[56:59], v[160:163], v[200:203], v[56:59]
	v_mfma_f32_16x16x32_bf16 v[48:51], v[152:155], v[208:211], v[48:51]
	v_mfma_f32_16x16x32_bf16 v[40:43], v[160:163], v[208:211], v[40:43]
	v_mfma_f32_16x16x32_bf16 v[32:35], v[152:155], v[216:219], v[32:35]
	v_mfma_f32_16x16x32_bf16 v[24:27], v[160:163], v[216:219], v[24:27]
	v_mfma_f32_16x16x32_bf16 v[16:19], v[152:155], v[224:227], v[16:19]
	v_mfma_f32_16x16x32_bf16 v[8:11], v[160:163], v[224:227], v[8:11]
	v_mfma_f32_16x16x32_bf16 v[60:63], v[156:159], v[204:207], v[60:63]
	v_mfma_f32_16x16x32_bf16 v[56:59], v[164:167], v[204:207], v[56:59]
	v_mfma_f32_16x16x32_bf16 v[48:51], v[156:159], v[212:215], v[48:51]
	v_mfma_f32_16x16x32_bf16 v[40:43], v[164:167], v[212:215], v[40:43]
	v_mfma_f32_16x16x32_bf16 v[32:35], v[156:159], v[220:223], v[32:35]
	v_mfma_f32_16x16x32_bf16 v[24:27], v[164:167], v[220:223], v[24:27]
	v_mfma_f32_16x16x32_bf16 v[16:19], v[156:159], v[228:231], v[16:19]
	v_mfma_f32_16x16x32_bf16 v[8:11], v[164:167], v[228:231], v[8:11]
	s_setprio 0
	s_setprio 1
	v_mfma_f32_16x16x32_bf16 v[52:55], v[184:187], v[200:203], v[52:55]
	v_mfma_f32_16x16x32_bf16 v[44:47], v[192:195], v[200:203], v[44:47]
	v_mfma_f32_16x16x32_bf16 v[36:39], v[184:187], v[208:211], v[36:39]
	v_mfma_f32_16x16x32_bf16 v[28:31], v[192:195], v[208:211], v[28:31]
	v_mfma_f32_16x16x32_bf16 v[20:23], v[184:187], v[216:219], v[20:23]
	v_mfma_f32_16x16x32_bf16 v[12:15], v[192:195], v[216:219], v[12:15]
	v_mfma_f32_16x16x32_bf16 v[4:7], v[184:187], v[224:227], v[4:7]
	v_mfma_f32_16x16x32_bf16 v[0:3], v[192:195], v[224:227], v[0:3]
	v_mfma_f32_16x16x32_bf16 v[52:55], v[188:191], v[204:207], v[52:55]
	v_mfma_f32_16x16x32_bf16 v[44:47], v[196:199], v[204:207], v[44:47]
	v_mfma_f32_16x16x32_bf16 v[36:39], v[188:191], v[212:215], v[36:39]
	v_mfma_f32_16x16x32_bf16 v[28:31], v[196:199], v[212:215], v[28:31]
	v_mfma_f32_16x16x32_bf16 v[20:23], v[188:191], v[220:223], v[20:23]
	v_mfma_f32_16x16x32_bf16 v[12:15], v[196:199], v[220:223], v[12:15]
	s_setprio 2
	s_barrier
	v_mfma_f32_16x16x32_bf16 v[4:7], v[188:191], v[228:231], v[4:7]
	v_mfma_f32_16x16x32_bf16 v[0:3], v[196:199], v[228:231], v[0:3]
	s_setprio 0
	v_add_u32_e32 v151, s14, v148
	ds_read_b128 v[152:155], v151
	ds_read_b128 v[156:159], v151 offset:1024
	ds_read_b128 v[160:163], v151 offset:2048
	ds_read_b128 v[164:167], v151 offset:3072
	v_add_u32_e32 v151, s13, v148
	ds_read_b128 v[184:187], v151
	ds_read_b128 v[188:191], v151 offset:1024
	ds_read_b128 v[192:195], v151 offset:2048
	ds_read_b128 v[196:199], v151 offset:3072
	s_mov_b32 m0, s66
	v_lshl_add_u64 v[234:235], s[56:57], 0, v[144:145]
	ds_read_b128 v[200:203], v150 offset:32768
	ds_read_b128 v[204:207], v150 offset:33792
	ds_read_b128 v[208:211], v150 offset:34816
	ds_read_b128 v[212:215], v150 offset:35840
	ds_read_b128 v[216:219], v150 offset:36864
	ds_read_b128 v[220:223], v150 offset:37888
	ds_read_b128 v[224:227], v150 offset:38912
	ds_read_b128 v[228:231], v150 offset:39936
	global_load_lds_dwordx4 v[234:235], off
	v_lshl_add_u64 v[234:235], s[56:57], 0, v[140:141]
	s_mov_b32 m0, s67
	s_nop 0
	global_load_lds_dwordx4 v[234:235], off
	s_waitcnt vmcnt(8)
	s_waitcnt lgkmcnt(0)
	s_setprio 1
	s_barrier
	v_mfma_f32_16x16x32_bf16 v[124:127], v[152:155], v[200:203], v[124:127]
	v_mfma_f32_16x16x32_bf16 v[120:123], v[160:163], v[200:203], v[120:123]
	v_mfma_f32_16x16x32_bf16 v[112:115], v[152:155], v[208:211], v[112:115]
	v_mfma_f32_16x16x32_bf16 v[104:107], v[160:163], v[208:211], v[104:107]
	v_mfma_f32_16x16x32_bf16 v[96:99], v[152:155], v[216:219], v[96:99]
	v_mfma_f32_16x16x32_bf16 v[88:91], v[160:163], v[216:219], v[88:91]
	v_mfma_f32_16x16x32_bf16 v[80:83], v[152:155], v[224:227], v[80:83]
	v_mfma_f32_16x16x32_bf16 v[72:75], v[160:163], v[224:227], v[72:75]
	v_mfma_f32_16x16x32_bf16 v[124:127], v[156:159], v[204:207], v[124:127]
	v_mfma_f32_16x16x32_bf16 v[120:123], v[164:167], v[204:207], v[120:123]
	v_mfma_f32_16x16x32_bf16 v[112:115], v[156:159], v[212:215], v[112:115]
	v_mfma_f32_16x16x32_bf16 v[104:107], v[164:167], v[212:215], v[104:107]
	v_mfma_f32_16x16x32_bf16 v[96:99], v[156:159], v[220:223], v[96:99]
	v_mfma_f32_16x16x32_bf16 v[88:91], v[164:167], v[220:223], v[88:91]
	v_mfma_f32_16x16x32_bf16 v[80:83], v[156:159], v[228:231], v[80:83]
	v_mfma_f32_16x16x32_bf16 v[72:75], v[164:167], v[228:231], v[72:75]
	s_setprio 0
	s_setprio 1
	v_mfma_f32_16x16x32_bf16 v[116:119], v[184:187], v[200:203], v[116:119]
	v_mfma_f32_16x16x32_bf16 v[108:111], v[192:195], v[200:203], v[108:111]
	v_mfma_f32_16x16x32_bf16 v[100:103], v[184:187], v[208:211], v[100:103]
	v_mfma_f32_16x16x32_bf16 v[92:95], v[192:195], v[208:211], v[92:95]
	v_mfma_f32_16x16x32_bf16 v[84:87], v[184:187], v[216:219], v[84:87]
	v_mfma_f32_16x16x32_bf16 v[76:79], v[192:195], v[216:219], v[76:79]
	v_mfma_f32_16x16x32_bf16 v[68:71], v[184:187], v[224:227], v[68:71]
	v_mfma_f32_16x16x32_bf16 v[64:67], v[192:195], v[224:227], v[64:67]
	v_mfma_f32_16x16x32_bf16 v[116:119], v[188:191], v[204:207], v[116:119]
	v_mfma_f32_16x16x32_bf16 v[108:111], v[196:199], v[204:207], v[108:111]
	v_mfma_f32_16x16x32_bf16 v[100:103], v[188:191], v[212:215], v[100:103]
	v_mfma_f32_16x16x32_bf16 v[92:95], v[196:199], v[212:215], v[92:95]
	v_mfma_f32_16x16x32_bf16 v[84:87], v[188:191], v[220:223], v[84:87]
	v_mfma_f32_16x16x32_bf16 v[76:79], v[196:199], v[220:223], v[76:79]
	s_setprio 2
	s_barrier
; #define PG8_STAGE(bufoff, gbase, voff) do { _Pragma("unroll") for (int _i = 0; _i < 2; ++_i) \
;         __builtin_amdgcn_global_load_lds((const unsigned*)((const char*)(gbase) + (voff)[_i]), (LAS unsigned*)(lds + (bufoff) + ldsw + _i * 8192), 16, 0, 0); } while (0)
; #define PG8_LDA(dst, b, h) do { _Pragma("unroll") for (int m = 0; m < 4; ++m) _Pragma("unroll") for (int k = 0; k < 2; ++k) dst[m][k] = *(const LAS bf16x8*)(lds + PG8_SA(b, h) + aoff + m * 2048 + k * 1024); } while (0)
; #define PG8_MMA(ai, bj, At, Bt) do { __builtin_amdgcn_s_setprio(1); _Pragma("unroll") for (int m = 0; m < 4; ++m) _Pragma("unroll") for (int n = 0; n < 2; ++n) _Pragma("unroll") for (int k = 0; k < 2; ++k) \
;         acc[ai][bj][m][n] = __builtin_amdgcn_mfma_f32_16x16x32_bf16(Bt[n][k], At[m][k], acc[ai][bj][m][n], 0, 0, 0); __builtin_amdgcn_s_setprio(0); } while (0)
; #define PG8_WAIT_V(n) asm volatile("s_waitcnt vmcnt(" #n ")" ::: "memory")
; #define PG8_WAIT_L(n) asm volatile("s_waitcnt lgkmcnt(" #n ")" ::: "memory")
; #define PG8_BAR __builtin_amdgcn_s_barrier()
; #define PG8_SCHED __builtin_amdgcn_sched_barrier(0)
; template <class Epi, class Sched>
; __device__ __forceinline__ void gemm_phase(LAS unsigned char* lds, const int K, const Sched& S, const Epi& E) {
;     ...
;             PG8_LDA(At, 1, 1); PG8_STAGE(PG8_SB(1, 0), b3, voffB); PG8_STAGE(PG8_SB(1, 1), b3 + hstep, voffB); PG8_STAGE(PG8_SA(1, 0), a3, voffA);
;             PG8_WAIT_V(8); PG8_WAIT_L(0); PG8_BAR; PG8_MMA(1, 0, At, B0); PG8_MMA(1, 1, At, B1); PG8_BAR; PG8_SCHED;
;         }
;         if (wr == 0) PG8_BAR;
	v_mfma_f32_16x16x32_bf16 v[68:71], v[188:191], v[228:231], v[68:71]
	v_mfma_f32_16x16x32_bf16 v[64:67], v[196:199], v[228:231], v[64:67]
	s_setprio 0
	s_mov_b32 m0, s12
	v_lshl_add_u64 v[146:147], v[146:147], 0, s[36:37]
	ds_read_b128 v[200:203], v150 offset:49152
	ds_read_b128 v[204:207], v150 offset:50176
	ds_read_b128 v[208:211], v150 offset:51200
	ds_read_b128 v[212:215], v150 offset:52224
	ds_read_b128 v[216:219], v150 offset:53248
	ds_read_b128 v[220:223], v150 offset:54272
	ds_read_b128 v[224:227], v150 offset:55296
	ds_read_b128 v[228:231], v150 offset:56320
	global_load_lds_dwordx4 v[146:147], off
	v_lshl_add_u64 v[146:147], v[180:181], 0, s[36:37]
	s_mov_b32 m0, s11
	s_nop 0
	global_load_lds_dwordx4 v[146:147], off
	v_lshl_add_u64 v[146:147], s[54:55], 0, v[142:143]
	s_mov_b32 m0, s25
	s_nop 0
	global_load_lds_dwordx4 v[146:147], off
	v_lshl_add_u64 v[146:147], s[54:55], 0, v[138:139]
	s_mov_b32 m0, s21
	s_nop 0
	global_load_lds_dwordx4 v[146:147], off
	v_lshl_add_u64 v[146:147], v[182:183], 0, s[36:37]
	s_mov_b32 m0, s0
	s_nop 0
	global_load_lds_dwordx4 v[146:147], off
	v_lshl_add_u64 v[146:147], v[232:233], 0, s[36:37]
	s_mov_b32 m0, s1
	s_nop 0
	global_load_lds_dwordx4 v[146:147], off
	s_waitcnt vmcnt(8)
	s_waitcnt lgkmcnt(0)
	s_setprio 1
	s_barrier
	v_mfma_f32_16x16x32_bf16 v[60:63], v[152:155], v[200:203], v[60:63]
	v_mfma_f32_16x16x32_bf16 v[56:59], v[160:163], v[200:203], v[56:59]
	v_mfma_f32_16x16x32_bf16 v[48:51], v[152:155], v[208:211], v[48:51]
	v_mfma_f32_16x16x32_bf16 v[40:43], v[160:163], v[208:211], v[40:43]
	v_mfma_f32_16x16x32_bf16 v[32:35], v[152:155], v[216:219], v[32:35]
	v_mfma_f32_16x16x32_bf16 v[24:27], v[160:163], v[216:219], v[24:27]
	v_mfma_f32_16x16x32_bf16 v[16:19], v[152:155], v[224:227], v[16:19]
	v_mfma_f32_16x16x32_bf16 v[8:11], v[160:163], v[224:227], v[8:11]
	v_mfma_f32_16x16x32_bf16 v[60:63], v[156:159], v[204:207], v[60:63]
	v_mfma_f32_16x16x32_bf16 v[56:59], v[164:167], v[204:207], v[56:59]
	v_mfma_f32_16x16x32_bf16 v[48:51], v[156:159], v[212:215], v[48:51]
	v_mfma_f32_16x16x32_bf16 v[40:43], v[164:167], v[212:215], v[40:43]
	v_mfma_f32_16x16x32_bf16 v[32:35], v[156:159], v[220:223], v[32:35]
	v_mfma_f32_16x16x32_bf16 v[24:27], v[164:167], v[220:223], v[24:27]
	v_mfma_f32_16x16x32_bf16 v[16:19], v[156:159], v[228:231], v[16:19]
	v_mfma_f32_16x16x32_bf16 v[8:11], v[164:167], v[228:231], v[8:11]
	s_setprio 0
	s_setprio 1
	v_mfma_f32_16x16x32_bf16 v[52:55], v[184:187], v[200:203], v[52:55]
	v_mfma_f32_16x16x32_bf16 v[44:47], v[192:195], v[200:203], v[44:47]
	v_mfma_f32_16x16x32_bf16 v[36:39], v[184:187], v[208:211], v[36:39]
	v_mfma_f32_16x16x32_bf16 v[28:31], v[192:195], v[208:211], v[28:31]
	v_mfma_f32_16x16x32_bf16 v[20:23], v[184:187], v[216:219], v[20:23]
	v_mfma_f32_16x16x32_bf16 v[12:15], v[192:195], v[216:219], v[12:15]
	v_mfma_f32_16x16x32_bf16 v[4:7], v[184:187], v[224:227], v[4:7]
	v_mfma_f32_16x16x32_bf16 v[0:3], v[192:195], v[224:227], v[0:3]
	v_mfma_f32_16x16x32_bf16 v[52:55], v[188:191], v[204:207], v[52:55]
	v_mfma_f32_16x16x32_bf16 v[44:47], v[196:199], v[204:207], v[44:47]
	v_mfma_f32_16x16x32_bf16 v[36:39], v[188:191], v[212:215], v[36:39]
	v_mfma_f32_16x16x32_bf16 v[28:31], v[196:199], v[212:215], v[28:31]
	v_mfma_f32_16x16x32_bf16 v[20:23], v[188:191], v[220:223], v[20:23]
	v_mfma_f32_16x16x32_bf16 v[12:15], v[196:199], v[220:223], v[12:15]
	s_setprio 2
	s_barrier
	v_mfma_f32_16x16x32_bf16 v[4:7], v[188:191], v[228:231], v[4:7]
	v_mfma_f32_16x16x32_bf16 v[0:3], v[196:199], v[228:231], v[0:3]
	s_setprio 0
	s_movk_i32 s11, 0x100
	s_andn2_b64 vcc, exec, s[52:53]
	s_mov_b64 s[54:55], -1
	s_mov_b64 s[52:53], 0
	s_cbranch_vccz .LBB0_533
	s_and_b64 vcc, exec, s[40:41]
	s_cbranch_vccz .LBB0_536
	s_barrier

; #define PG8_STAGE(bufoff, gbase, voff) do { _Pragma("unroll") for (int _i = 0; _i < 2; ++_i) \
;         __builtin_amdgcn_global_load_lds((const unsigned*)((const char*)(gbase) + (voff)[_i]), (LAS unsigned*)(lds + (bufoff) + ldsw + _i * 8192), 16, 0, 0); } while (0)
; #define PG8_LDA(dst, b, h) do { _Pragma("unroll") for (int m = 0; m < 4; ++m) _Pragma("unroll") for (int k = 0; k < 2; ++k) dst[m][k] = *(const LAS bf16x8*)(lds + PG8_SA(b, h) + aoff + m * 2048 + k * 1024); } while (0)
; #define PG8_LDB(dst, b, h) do { _Pragma("unroll") for (int n = 0; n < 2; ++n) _Pragma("unroll") for (int k = 0; k < 2; ++k) dst[n][k] = *(const LAS bf16x8*)(lds + PG8_SB(b, h) + boff + n * 2048 + k * 1024); } while (0)
; #define PG8_MMA(ai, bj, At, Bt) do { __builtin_amdgcn_s_setprio(1); _Pragma("unroll") for (int m = 0; m < 4; ++m) _Pragma("unroll") for (int n = 0; n < 2; ++n) _Pragma("unroll") for (int k = 0; k < 2; ++k) \
;         acc[ai][bj][m][n] = __builtin_amdgcn_mfma_f32_16x16x32_bf16(Bt[n][k], At[m][k], acc[ai][bj][m][n], 0, 0, 0); __builtin_amdgcn_s_setprio(0); } while (0)
; #define PG8_WAIT_V(n) asm volatile("s_waitcnt vmcnt(" #n ")" ::: "memory")
; #define PG8_WAIT_L(n) asm volatile("s_waitcnt lgkmcnt(" #n ")" ::: "memory")
; #define PG8_BAR __builtin_amdgcn_s_barrier()
; #define PG8_SCHED __builtin_amdgcn_sched_barrier(0)
; template <class Epi, class Sched>
; __device__ __forceinline__ void gemm_phase(LAS unsigned char* lds, const int K, const Sched& S, const Epi& E) {
;     ...
;             const bool last = (t == nt - 2);
;             const char* a1 = cA + (size_t)(t + 1) * kstep;
;             const char* a2 = last ? nA : cA + (size_t)(t + 2) * kstep; const char* b2 = last ? nB : cB + (size_t)(t + 2) * kstep;
;             const char* a3 = a2 + kstep; const char* b3 = b2 + kstep;
;             PG8_LDB(B0, 0, 0); PG8_LDB(B1, 0, 1); PG8_SCHED; PG8_LDA(At, 0, 0); PG8_STAGE(PG8_SA(1, 1), a1 + hstep, voffA);
;             PG8_WAIT_V(8); PG8_WAIT_L(0); PG8_BAR; PG8_MMA(0, 0, At, B0); PG8_MMA(0, 1, At, B1); PG8_BAR; PG8_SCHED;
;             PG8_LDA(At, 0, 1); PG8_STAGE(PG8_SB(0, 0), b2, voffB); PG8_STAGE(PG8_SB(0, 1), b2 + hstep, voffB); PG8_STAGE(PG8_SA(0, 0), a2, voffA);
;             PG8_WAIT_V(8); PG8_WAIT_L(0); PG8_BAR; PG8_MMA(1, 0, At, B0); PG8_MMA(1, 1, At, B1); PG8_BAR; PG8_SCHED;
.LBB0_812:
	s_add_i32 s16, s15, 2
	s_add_u32 s50, s8, 0x100
	s_addc_u32 s51, s9, 0
	s_add_i32 s17, 0, 0x10000
	s_cmp_eq_u32 s12, s15
	s_cselect_b32 s55, s4, s51
	s_cselect_b32 s54, s5, s50
	s_cselect_b32 s53, s10, s14
	s_cselect_b32 s52, s11, s13
	s_add_i32 s15, 0, 0x14000
	v_add_u32_e32 v158, s17, v164
	v_add_u32_e32 v162, s15, v164
	ds_read_b128 v[146:149], v158
	ds_read_b128 v[150:153], v158 offset:1024
	ds_read_b128 v[154:157], v158 offset:2048
	ds_read_b128 v[158:161], v158 offset:3072
	ds_read_b128 v[184:187], v162
	ds_read_b128 v[188:191], v162 offset:1024
	ds_read_b128 v[192:195], v162 offset:2048
	ds_read_b128 v[196:199], v162 offset:3072
	v_lshl_add_u64 v[162:163], s[8:9], 0, v[142:143]
	s_add_i32 m0, s26, 0xc000
	ds_read_b128 v[200:203], v166
	ds_read_b128 v[204:207], v166 offset:1024
	ds_read_b128 v[208:211], v166 offset:2048
	ds_read_b128 v[212:215], v166 offset:3072
	ds_read_b128 v[216:219], v166 offset:4096
	ds_read_b128 v[220:223], v166 offset:5120
	ds_read_b128 v[224:227], v166 offset:6144
	ds_read_b128 v[228:231], v166 offset:7168
	global_load_lds_dwordx4 v[162:163], off
	v_lshl_add_u64 v[162:163], s[8:9], 0, v[144:145]
	s_add_i32 m0, s26, 0xe000
	s_nop 0
	global_load_lds_dwordx4 v[162:163], off
	s_waitcnt vmcnt(8)
	s_waitcnt lgkmcnt(0)
	s_setprio 1
	s_barrier
	v_mfma_f32_16x16x32_bf16 v[124:127], v[146:149], v[200:203], v[124:127]
	v_mfma_f32_16x16x32_bf16 v[92:95], v[154:157], v[200:203], v[92:95]
	v_mfma_f32_16x16x32_bf16 v[120:123], v[146:149], v[208:211], v[120:123]
	v_mfma_f32_16x16x32_bf16 v[88:91], v[154:157], v[208:211], v[88:91]
	v_mfma_f32_16x16x32_bf16 v[116:119], v[146:149], v[216:219], v[116:119]
	v_mfma_f32_16x16x32_bf16 v[84:87], v[154:157], v[216:219], v[84:87]
	v_mfma_f32_16x16x32_bf16 v[112:115], v[146:149], v[224:227], v[112:115]
	v_mfma_f32_16x16x32_bf16 v[80:83], v[154:157], v[224:227], v[80:83]
	v_mfma_f32_16x16x32_bf16 v[124:127], v[150:153], v[204:207], v[124:127]
	v_mfma_f32_16x16x32_bf16 v[92:95], v[158:161], v[204:207], v[92:95]
	v_mfma_f32_16x16x32_bf16 v[120:123], v[150:153], v[212:215], v[120:123]
	v_mfma_f32_16x16x32_bf16 v[88:91], v[158:161], v[212:215], v[88:91]
	v_mfma_f32_16x16x32_bf16 v[116:119], v[150:153], v[220:223], v[116:119]
	v_mfma_f32_16x16x32_bf16 v[84:87], v[158:161], v[220:223], v[84:87]
	v_mfma_f32_16x16x32_bf16 v[112:115], v[150:153], v[228:231], v[112:115]
	v_mfma_f32_16x16x32_bf16 v[80:83], v[158:161], v[228:231], v[80:83]
	s_setprio 0
	s_setprio 1
	v_mfma_f32_16x16x32_bf16 v[64:67], v[184:187], v[200:203], v[64:67]
	v_mfma_f32_16x16x32_bf16 v[40:43], v[192:195], v[200:203], v[40:43]
	v_mfma_f32_16x16x32_bf16 v[56:59], v[184:187], v[208:211], v[56:59]
	v_mfma_f32_16x16x32_bf16 v[32:35], v[192:195], v[208:211], v[32:35]
	v_mfma_f32_16x16x32_bf16 v[52:55], v[184:187], v[216:219], v[52:55]
	v_mfma_f32_16x16x32_bf16 v[24:27], v[192:195], v[216:219], v[24:27]
	v_mfma_f32_16x16x32_bf16 v[48:51], v[184:187], v[224:227], v[48:51]
	v_mfma_f32_16x16x32_bf16 v[16:19], v[192:195], v[224:227], v[16:19]
	v_mfma_f32_16x16x32_bf16 v[64:67], v[188:191], v[204:207], v[64:67]
	v_mfma_f32_16x16x32_bf16 v[40:43], v[196:199], v[204:207], v[40:43]
	v_mfma_f32_16x16x32_bf16 v[56:59], v[188:191], v[212:215], v[56:59]
	v_mfma_f32_16x16x32_bf16 v[32:35], v[196:199], v[212:215], v[32:35]
	v_mfma_f32_16x16x32_bf16 v[52:55], v[188:191], v[220:223], v[52:55]
	v_mfma_f32_16x16x32_bf16 v[24:27], v[196:199], v[220:223], v[24:27]
	s_setprio 2
	s_barrier
	v_mfma_f32_16x16x32_bf16 v[48:51], v[188:191], v[228:231], v[48:51]
	v_mfma_f32_16x16x32_bf16 v[16:19], v[196:199], v[228:231], v[16:19]
	s_setprio 0
	s_add_i32 s8, s17, s3
	v_lshl_add_u64 v[162:163], s[52:53], 0, v[128:129]
	s_mov_b32 m0, s8
	ds_read_b128 v[200:203], v166 offset:16384
	ds_read_b128 v[204:207], v166 offset:17408
	ds_read_b128 v[208:211], v166 offset:18432
	ds_read_b128 v[212:215], v166 offset:19456
	ds_read_b128 v[216:219], v166 offset:20480
	ds_read_b128 v[220:223], v166 offset:21504
	ds_read_b128 v[224:227], v166 offset:22528
	ds_read_b128 v[228:231], v166 offset:23552
	global_load_lds_dwordx4 v[162:163], off
	s_add_i32 m0, s8, 0x2000
	s_add_u32 s8, s52, 0x50000
	v_lshl_add_u64 v[180:181], s[52:53], 0, v[138:139]
	s_addc_u32 s9, s53, 0
	s_add_i32 s15, s15, s3
	global_load_lds_dwordx4 v[180:181], off
	v_lshl_add_u64 v[182:183], s[8:9], 0, v[128:129]
	s_mov_b32 m0, s15
	v_lshl_add_u64 v[232:233], s[54:55], 0, v[138:139]
	global_load_lds_dwordx4 v[182:183], off
	v_lshl_add_u64 v[182:183], s[8:9], 0, v[138:139]
	s_add_i32 m0, s15, 0x2000
	s_nop 0
	global_load_lds_dwordx4 v[182:183], off
	v_lshl_add_u64 v[182:183], s[54:55], 0, v[128:129]
	s_mov_b32 m0, s26
	s_nop 0
	global_load_lds_dwordx4 v[182:183], off
	s_mov_b32 m0, s27
	s_nop 0
	global_load_lds_dwordx4 v[232:233], off
	s_waitcnt vmcnt(8)
	s_waitcnt lgkmcnt(0)
	s_setprio 1
	s_barrier
; #define PG8_STAGE(bufoff, gbase, voff) do { _Pragma("unroll") for (int _i = 0; _i < 2; ++_i) \
;         __builtin_amdgcn_global_load_lds((const unsigned*)((const char*)(gbase) + (voff)[_i]), (LAS unsigned*)(lds + (bufoff) + ldsw + _i * 8192), 16, 0, 0); } while (0)
; #define PG8_LDA(dst, b, h) do { _Pragma("unroll") for (int m = 0; m < 4; ++m) _Pragma("unroll") for (int k = 0; k < 2; ++k) dst[m][k] = *(const LAS bf16x8*)(lds + PG8_SA(b, h) + aoff + m * 2048 + k * 1024); } while (0)
; #define PG8_LDB(dst, b, h) do { _Pragma("unroll") for (int n = 0; n < 2; ++n) _Pragma("unroll") for (int k = 0; k < 2; ++k) dst[n][k] = *(const LAS bf16x8*)(lds + PG8_SB(b, h) + boff + n * 2048 + k * 1024); } while (0)
; #define PG8_MMA(ai, bj, At, Bt) do { __builtin_amdgcn_s_setprio(1); _Pragma("unroll") for (int m = 0; m < 4; ++m) _Pragma("unroll") for (int n = 0; n < 2; ++n) _Pragma("unroll") for (int k = 0; k < 2; ++k) \
;         acc[ai][bj][m][n] = __builtin_amdgcn_mfma_f32_16x16x32_bf16(Bt[n][k], At[m][k], acc[ai][bj][m][n], 0, 0, 0); __builtin_amdgcn_s_setprio(0); } while (0)
; #define PG8_WAIT_V(n) asm volatile("s_waitcnt vmcnt(" #n ")" ::: "memory")
; #define PG8_WAIT_L(n) asm volatile("s_waitcnt lgkmcnt(" #n ")" ::: "memory")
; #define PG8_BAR __builtin_amdgcn_s_barrier()
; #define PG8_SCHED __builtin_amdgcn_sched_barrier(0)
; template <class Epi, class Sched>
; __device__ __forceinline__ void gemm_phase(LAS unsigned char* lds, const int K, const Sched& S, const Epi& E) {
;     ...
;             PG8_WAIT_V(8); PG8_WAIT_L(0); PG8_BAR; PG8_MMA(1, 0, At, B0); PG8_MMA(1, 1, At, B1); PG8_BAR; PG8_SCHED;
;             PG8_LDB(B0, 1, 0); PG8_LDB(B1, 1, 1); PG8_SCHED; PG8_LDA(At, 1, 0); PG8_STAGE(PG8_SA(0, 1), a2 + hstep, voffA);
;             PG8_WAIT_V(8); PG8_WAIT_L(0); PG8_BAR; PG8_MMA(0, 0, At, B0); PG8_MMA(0, 1, At, B1); PG8_BAR; PG8_SCHED;
;             PG8_LDA(At, 1, 1); PG8_STAGE(PG8_SB(1, 0), b3, voffB); PG8_STAGE(PG8_SB(1, 1), b3 + hstep, voffB); PG8_STAGE(PG8_SA(1, 0), a3, voffA);
;             PG8_WAIT_V(8); PG8_WAIT_L(0); PG8_BAR; PG8_MMA(1, 0, At, B0); PG8_MMA(1, 1, At, B1); PG8_BAR; PG8_SCHED;
	v_mfma_f32_16x16x32_bf16 v[108:111], v[146:149], v[200:203], v[108:111]
	v_mfma_f32_16x16x32_bf16 v[76:79], v[154:157], v[200:203], v[76:79]
	v_mfma_f32_16x16x32_bf16 v[104:107], v[146:149], v[208:211], v[104:107]
	v_mfma_f32_16x16x32_bf16 v[72:75], v[154:157], v[208:211], v[72:75]
	v_mfma_f32_16x16x32_bf16 v[100:103], v[146:149], v[216:219], v[100:103]
	v_mfma_f32_16x16x32_bf16 v[68:71], v[154:157], v[216:219], v[68:71]
	v_mfma_f32_16x16x32_bf16 v[96:99], v[146:149], v[224:227], v[96:99]
	v_mfma_f32_16x16x32_bf16 v[60:63], v[154:157], v[224:227], v[60:63]
	v_mfma_f32_16x16x32_bf16 v[108:111], v[150:153], v[204:207], v[108:111]
	v_mfma_f32_16x16x32_bf16 v[76:79], v[158:161], v[204:207], v[76:79]
	v_mfma_f32_16x16x32_bf16 v[104:107], v[150:153], v[212:215], v[104:107]
	v_mfma_f32_16x16x32_bf16 v[72:75], v[158:161], v[212:215], v[72:75]
	v_mfma_f32_16x16x32_bf16 v[100:103], v[150:153], v[220:223], v[100:103]
	v_mfma_f32_16x16x32_bf16 v[68:71], v[158:161], v[220:223], v[68:71]
	v_mfma_f32_16x16x32_bf16 v[96:99], v[150:153], v[228:231], v[96:99]
	v_mfma_f32_16x16x32_bf16 v[60:63], v[158:161], v[228:231], v[60:63]
	s_setprio 0
	s_setprio 1
	v_mfma_f32_16x16x32_bf16 v[44:47], v[184:187], v[200:203], v[44:47]
	v_mfma_f32_16x16x32_bf16 v[12:15], v[192:195], v[200:203], v[12:15]
	v_mfma_f32_16x16x32_bf16 v[36:39], v[184:187], v[208:211], v[36:39]
	v_mfma_f32_16x16x32_bf16 v[8:11], v[192:195], v[208:211], v[8:11]
	v_mfma_f32_16x16x32_bf16 v[28:31], v[184:187], v[216:219], v[28:31]
	v_mfma_f32_16x16x32_bf16 v[4:7], v[192:195], v[216:219], v[4:7]
	v_mfma_f32_16x16x32_bf16 v[20:23], v[184:187], v[224:227], v[20:23]
	v_mfma_f32_16x16x32_bf16 v[0:3], v[192:195], v[224:227], v[0:3]
	v_mfma_f32_16x16x32_bf16 v[44:47], v[188:191], v[204:207], v[44:47]
	v_mfma_f32_16x16x32_bf16 v[12:15], v[196:199], v[204:207], v[12:15]
	v_mfma_f32_16x16x32_bf16 v[36:39], v[188:191], v[212:215], v[36:39]
	v_mfma_f32_16x16x32_bf16 v[8:11], v[196:199], v[212:215], v[8:11]
	v_mfma_f32_16x16x32_bf16 v[28:31], v[188:191], v[220:223], v[28:31]
	v_mfma_f32_16x16x32_bf16 v[4:7], v[196:199], v[220:223], v[4:7]
	s_setprio 2
	s_barrier
	v_mfma_f32_16x16x32_bf16 v[20:23], v[188:191], v[228:231], v[20:23]
	v_mfma_f32_16x16x32_bf16 v[0:3], v[196:199], v[228:231], v[0:3]
	s_setprio 0
	s_add_i32 s15, 0, 0x18000
	s_add_i32 s17, 0, 0x1c000
	v_add_u32_e32 v158, s15, v164
	v_add_u32_e32 v167, s17, v164
	ds_read_b128 v[146:149], v158
	ds_read_b128 v[150:153], v158 offset:1024
	ds_read_b128 v[154:157], v158 offset:2048
	ds_read_b128 v[158:161], v158 offset:3072
	ds_read_b128 v[184:187], v167
	ds_read_b128 v[188:191], v167 offset:1024
	ds_read_b128 v[192:195], v167 offset:2048
	ds_read_b128 v[196:199], v167 offset:3072
	s_add_u32 s8, s54, 0x50000
	s_addc_u32 s9, s55, 0
	s_mov_b32 m0, s56
	v_lshl_add_u64 v[234:235], s[8:9], 0, v[128:129]
	ds_read_b128 v[200:203], v166 offset:32768
	ds_read_b128 v[204:207], v166 offset:33792
	ds_read_b128 v[208:211], v166 offset:34816
	ds_read_b128 v[212:215], v166 offset:35840
	ds_read_b128 v[216:219], v166 offset:36864
	ds_read_b128 v[220:223], v166 offset:37888
	ds_read_b128 v[224:227], v166 offset:38912
	ds_read_b128 v[228:231], v166 offset:39936
	global_load_lds_dwordx4 v[234:235], off
	v_lshl_add_u64 v[234:235], s[8:9], 0, v[138:139]
	s_mov_b32 m0, s57
	s_nop 0
	global_load_lds_dwordx4 v[234:235], off
	s_waitcnt vmcnt(8)
	s_waitcnt lgkmcnt(0)
	s_setprio 1
	s_barrier
	v_mfma_f32_16x16x32_bf16 v[124:127], v[146:149], v[200:203], v[124:127]
	v_mfma_f32_16x16x32_bf16 v[92:95], v[154:157], v[200:203], v[92:95]
	v_mfma_f32_16x16x32_bf16 v[120:123], v[146:149], v[208:211], v[120:123]
	v_mfma_f32_16x16x32_bf16 v[88:91], v[154:157], v[208:211], v[88:91]
	v_mfma_f32_16x16x32_bf16 v[116:119], v[146:149], v[216:219], v[116:119]
	v_mfma_f32_16x16x32_bf16 v[84:87], v[154:157], v[216:219], v[84:87]
	v_mfma_f32_16x16x32_bf16 v[112:115], v[146:149], v[224:227], v[112:115]
	v_mfma_f32_16x16x32_bf16 v[80:83], v[154:157], v[224:227], v[80:83]
	v_mfma_f32_16x16x32_bf16 v[124:127], v[150:153], v[204:207], v[124:127]
	v_mfma_f32_16x16x32_bf16 v[92:95], v[158:161], v[204:207], v[92:95]
	v_mfma_f32_16x16x32_bf16 v[120:123], v[150:153], v[212:215], v[120:123]
	v_mfma_f32_16x16x32_bf16 v[88:91], v[158:161], v[212:215], v[88:91]
	v_mfma_f32_16x16x32_bf16 v[116:119], v[150:153], v[220:223], v[116:119]
	v_mfma_f32_16x16x32_bf16 v[84:87], v[158:161], v[220:223], v[84:87]
	v_mfma_f32_16x16x32_bf16 v[112:115], v[150:153], v[228:231], v[112:115]
	v_mfma_f32_16x16x32_bf16 v[80:83], v[158:161], v[228:231], v[80:83]
	s_setprio 0
	s_setprio 1
	v_mfma_f32_16x16x32_bf16 v[64:67], v[184:187], v[200:203], v[64:67]
	v_mfma_f32_16x16x32_bf16 v[40:43], v[192:195], v[200:203], v[40:43]
	v_mfma_f32_16x16x32_bf16 v[56:59], v[184:187], v[208:211], v[56:59]
	v_mfma_f32_16x16x32_bf16 v[32:35], v[192:195], v[208:211], v[32:35]
	v_mfma_f32_16x16x32_bf16 v[52:55], v[184:187], v[216:219], v[52:55]
	v_mfma_f32_16x16x32_bf16 v[24:27], v[192:195], v[216:219], v[24:27]
	v_mfma_f32_16x16x32_bf16 v[48:51], v[184:187], v[224:227], v[48:51]
	v_mfma_f32_16x16x32_bf16 v[16:19], v[192:195], v[224:227], v[16:19]
	v_mfma_f32_16x16x32_bf16 v[64:67], v[188:191], v[204:207], v[64:67]
	v_mfma_f32_16x16x32_bf16 v[40:43], v[196:199], v[204:207], v[40:43]
	v_mfma_f32_16x16x32_bf16 v[56:59], v[188:191], v[212:215], v[56:59]
	v_mfma_f32_16x16x32_bf16 v[32:35], v[196:199], v[212:215], v[32:35]
	v_mfma_f32_16x16x32_bf16 v[52:55], v[188:191], v[220:223], v[52:55]
	v_mfma_f32_16x16x32_bf16 v[24:27], v[196:199], v[220:223], v[24:27]
	s_setprio 2
	s_barrier
; #define PG8_STAGE(bufoff, gbase, voff) do { _Pragma("unroll") for (int _i = 0; _i < 2; ++_i) \
;         __builtin_amdgcn_global_load_lds((const unsigned*)((const char*)(gbase) + (voff)[_i]), (LAS unsigned*)(lds + (bufoff) + ldsw + _i * 8192), 16, 0, 0); } while (0)
; #define PG8_LDA(dst, b, h) do { _Pragma("unroll") for (int m = 0; m < 4; ++m) _Pragma("unroll") for (int k = 0; k < 2; ++k) dst[m][k] = *(const LAS bf16x8*)(lds + PG8_SA(b, h) + aoff + m * 2048 + k * 1024); } while (0)
; #define PG8_MMA(ai, bj, At, Bt) do { __builtin_amdgcn_s_setprio(1); _Pragma("unroll") for (int m = 0; m < 4; ++m) _Pragma("unroll") for (int n = 0; n < 2; ++n) _Pragma("unroll") for (int k = 0; k < 2; ++k) \
;         acc[ai][bj][m][n] = __builtin_amdgcn_mfma_f32_16x16x32_bf16(Bt[n][k], At[m][k], acc[ai][bj][m][n], 0, 0, 0); __builtin_amdgcn_s_setprio(0); } while (0)
; #define PG8_WAIT_V(n) asm volatile("s_waitcnt vmcnt(" #n ")" ::: "memory")
; #define PG8_WAIT_L(n) asm volatile("s_waitcnt lgkmcnt(" #n ")" ::: "memory")
; #define PG8_BAR __builtin_amdgcn_s_barrier()
; #define PG8_SCHED __builtin_amdgcn_sched_barrier(0)
; template <class Epi, class Sched>
; __device__ __forceinline__ void gemm_phase(LAS unsigned char* lds, const int K, const Sched& S, const Epi& E) {
;     ...
;             PG8_WAIT_V(8); PG8_WAIT_L(0); PG8_BAR; PG8_MMA(0, 0, At, B0); PG8_MMA(0, 1, At, B1); PG8_BAR; PG8_SCHED;
;             PG8_LDA(At, 1, 1); PG8_STAGE(PG8_SB(1, 0), b3, voffB); PG8_STAGE(PG8_SB(1, 1), b3 + hstep, voffB); PG8_STAGE(PG8_SA(1, 0), a3, voffA);
;             PG8_WAIT_V(8); PG8_WAIT_L(0); PG8_BAR; PG8_MMA(1, 0, At, B0); PG8_MMA(1, 1, At, B1); PG8_BAR; PG8_SCHED;
;         }
;         if (wr == 0) PG8_BAR;
	v_mfma_f32_16x16x32_bf16 v[48:51], v[188:191], v[228:231], v[48:51]
	v_mfma_f32_16x16x32_bf16 v[16:19], v[196:199], v[228:231], v[16:19]
	s_setprio 0
	s_add_i32 s8, s15, s3
	v_lshl_add_u64 v[162:163], v[162:163], 0, s[36:37]
	s_mov_b32 m0, s8
	ds_read_b128 v[200:203], v166 offset:49152
	ds_read_b128 v[204:207], v166 offset:50176
	ds_read_b128 v[208:211], v166 offset:51200
	ds_read_b128 v[212:215], v166 offset:52224
	ds_read_b128 v[216:219], v166 offset:53248
	ds_read_b128 v[220:223], v166 offset:54272
	ds_read_b128 v[224:227], v166 offset:55296
	ds_read_b128 v[228:231], v166 offset:56320
	global_load_lds_dwordx4 v[162:163], off
	s_add_i32 m0, s8, 0x2000
	s_add_u32 s8, s52, 0x50080
	v_lshl_add_u64 v[162:163], v[180:181], 0, s[36:37]
	s_addc_u32 s9, s53, 0
	s_add_i32 s15, s17, s3
	global_load_lds_dwordx4 v[162:163], off
	v_lshl_add_u64 v[162:163], s[8:9], 0, v[128:129]
	s_mov_b32 m0, s15
	s_nop 0
	global_load_lds_dwordx4 v[162:163], off
	v_lshl_add_u64 v[162:163], s[8:9], 0, v[138:139]
	s_add_i32 m0, s15, 0x2000
	s_nop 0
	global_load_lds_dwordx4 v[162:163], off
	v_lshl_add_u64 v[162:163], v[182:183], 0, s[36:37]
	s_mov_b32 m0, s58
	s_nop 0
	global_load_lds_dwordx4 v[162:163], off
	v_lshl_add_u64 v[162:163], v[232:233], 0, s[36:37]
	s_mov_b32 m0, s59
	s_nop 0
	global_load_lds_dwordx4 v[162:163], off
	s_waitcnt vmcnt(8)
	s_waitcnt lgkmcnt(0)
	s_setprio 1
	s_barrier
	v_mfma_f32_16x16x32_bf16 v[108:111], v[146:149], v[200:203], v[108:111]
	v_mfma_f32_16x16x32_bf16 v[76:79], v[154:157], v[200:203], v[76:79]
	v_mfma_f32_16x16x32_bf16 v[104:107], v[146:149], v[208:211], v[104:107]
	v_mfma_f32_16x16x32_bf16 v[72:75], v[154:157], v[208:211], v[72:75]
	v_mfma_f32_16x16x32_bf16 v[100:103], v[146:149], v[216:219], v[100:103]
	v_mfma_f32_16x16x32_bf16 v[68:71], v[154:157], v[216:219], v[68:71]
	v_mfma_f32_16x16x32_bf16 v[96:99], v[146:149], v[224:227], v[96:99]
	v_mfma_f32_16x16x32_bf16 v[60:63], v[154:157], v[224:227], v[60:63]
	v_mfma_f32_16x16x32_bf16 v[108:111], v[150:153], v[204:207], v[108:111]
	v_mfma_f32_16x16x32_bf16 v[76:79], v[158:161], v[204:207], v[76:79]
	v_mfma_f32_16x16x32_bf16 v[104:107], v[150:153], v[212:215], v[104:107]
	v_mfma_f32_16x16x32_bf16 v[72:75], v[158:161], v[212:215], v[72:75]
	v_mfma_f32_16x16x32_bf16 v[100:103], v[150:153], v[220:223], v[100:103]
	v_mfma_f32_16x16x32_bf16 v[68:71], v[158:161], v[220:223], v[68:71]
	v_mfma_f32_16x16x32_bf16 v[96:99], v[150:153], v[228:231], v[96:99]
	v_mfma_f32_16x16x32_bf16 v[60:63], v[158:161], v[228:231], v[60:63]
	s_setprio 0
	s_setprio 1
	v_mfma_f32_16x16x32_bf16 v[44:47], v[184:187], v[200:203], v[44:47]
	v_mfma_f32_16x16x32_bf16 v[12:15], v[192:195], v[200:203], v[12:15]
	v_mfma_f32_16x16x32_bf16 v[36:39], v[184:187], v[208:211], v[36:39]
	v_mfma_f32_16x16x32_bf16 v[8:11], v[192:195], v[208:211], v[8:11]
	v_mfma_f32_16x16x32_bf16 v[28:31], v[184:187], v[216:219], v[28:31]
	v_mfma_f32_16x16x32_bf16 v[4:7], v[192:195], v[216:219], v[4:7]
	v_mfma_f32_16x16x32_bf16 v[20:23], v[184:187], v[224:227], v[20:23]
	v_mfma_f32_16x16x32_bf16 v[0:3], v[192:195], v[224:227], v[0:3]
	v_mfma_f32_16x16x32_bf16 v[44:47], v[188:191], v[204:207], v[44:47]
	v_mfma_f32_16x16x32_bf16 v[12:15], v[196:199], v[204:207], v[12:15]
	v_mfma_f32_16x16x32_bf16 v[36:39], v[188:191], v[212:215], v[36:39]
	v_mfma_f32_16x16x32_bf16 v[8:11], v[196:199], v[212:215], v[8:11]
	v_mfma_f32_16x16x32_bf16 v[28:31], v[188:191], v[220:223], v[28:31]
	v_mfma_f32_16x16x32_bf16 v[4:7], v[196:199], v[220:223], v[4:7]
	s_setprio 2
	s_barrier
	v_mfma_f32_16x16x32_bf16 v[20:23], v[188:191], v[228:231], v[20:23]
	v_mfma_f32_16x16x32_bf16 v[0:3], v[196:199], v[228:231], v[0:3]
	s_setprio 0
	s_add_u32 s13, s13, 0x100
	s_addc_u32 s14, s14, 0
	s_cmp_ge_i32 s16, s2
	s_mov_b64 s[8:9], s[50:51]
	s_mov_b32 s15, s16
	s_cbranch_scc0 .LBB0_812
	s_and_b64 vcc, exec, s[40:41]
	s_cbranch_vccz .LBB0_815
	s_barrier

; #define PG8_STAGE(bufoff, gbase, voff) do { _Pragma("unroll") for (int _i = 0; _i < 2; ++_i) \
;         __builtin_amdgcn_global_load_lds((const unsigned*)((const char*)(gbase) + (voff)[_i]), (LAS unsigned*)(lds + (bufoff) + ldsw + _i * 8192), 16, 0, 0); } while (0)
; #define PG8_LDA(dst, b, h) do { _Pragma("unroll") for (int m = 0; m < 4; ++m) _Pragma("unroll") for (int k = 0; k < 2; ++k) dst[m][k] = *(const LAS bf16x8*)(lds + PG8_SA(b, h) + aoff + m * 2048 + k * 1024); } while (0)
; #define PG8_LDB(dst, b, h) do { _Pragma("unroll") for (int n = 0; n < 2; ++n) _Pragma("unroll") for (int k = 0; k < 2; ++k) dst[n][k] = *(const LAS bf16x8*)(lds + PG8_SB(b, h) + boff + n * 2048 + k * 1024); } while (0)
; #define PG8_MMA(ai, bj, At, Bt) do { __builtin_amdgcn_s_setprio(1); _Pragma("unroll") for (int m = 0; m < 4; ++m) _Pragma("unroll") for (int n = 0; n < 2; ++n) _Pragma("unroll") for (int k = 0; k < 2; ++k) \
;         acc[ai][bj][m][n] = __builtin_amdgcn_mfma_f32_16x16x32_bf16(Bt[n][k], At[m][k], acc[ai][bj][m][n], 0, 0, 0); __builtin_amdgcn_s_setprio(0); } while (0)
; #define PG8_WAIT_V(n) asm volatile("s_waitcnt vmcnt(" #n ")" ::: "memory")
; #define PG8_WAIT_L(n) asm volatile("s_waitcnt lgkmcnt(" #n ")" ::: "memory")
; #define PG8_BAR __builtin_amdgcn_s_barrier()
; #define PG8_SCHED __builtin_amdgcn_sched_barrier(0)
; template <class Epi, class Sched>
; __device__ __forceinline__ void gemm_phase(LAS unsigned char* lds, const int K, const Sched& S, const Epi& E) {
;     ...
;         for (int t = 0; t < nt; t += 2) {
;             const bool last = (t == nt - 2);
;             const char* a1 = cA + (size_t)(t + 1) * kstep;
;             const char* a2 = last ? nA : cA + (size_t)(t + 2) * kstep; const char* b2 = last ? nB : cB + (size_t)(t + 2) * kstep;
;             const char* a3 = a2 + kstep; const char* b3 = b2 + kstep;
;             PG8_LDB(B0, 0, 0); PG8_LDB(B1, 0, 1); PG8_SCHED; PG8_LDA(At, 0, 0); PG8_STAGE(PG8_SA(1, 1), a1 + hstep, voffA);
;             PG8_WAIT_V(8); PG8_WAIT_L(0); PG8_BAR; PG8_MMA(0, 0, At, B0); PG8_MMA(0, 1, At, B1); PG8_BAR; PG8_SCHED;
;             PG8_LDA(At, 0, 1); PG8_STAGE(PG8_SB(0, 0), b2, voffB); PG8_STAGE(PG8_SB(0, 1), b2 + hstep, voffB); PG8_STAGE(PG8_SA(0, 0), a2, voffA);
;             PG8_WAIT_V(8); PG8_WAIT_L(0); PG8_BAR; PG8_MMA(1, 0, At, B0); PG8_MMA(1, 1, At, B1); PG8_BAR; PG8_SCHED;
.LBB0_963:
	s_add_u32 s5, s56, 0xfffc0080
	s_addc_u32 s9, s57, -1
	s_add_i32 s10, 0, 0x10000
	s_cmp_eq_u32 s4, 12
	s_cselect_b32 s61, s53, s9
	s_cselect_b32 s60, s52, s5
	v_add_u32_e32 v150, s10, v153
	s_cselect_b32 s59, s55, s2
	s_cselect_b32 s58, s54, s1
	s_add_i32 s5, 0, 0x14000
	ds_read_b128 v[156:159], v150
	ds_read_b128 v[160:163], v150 offset:1024
	ds_read_b128 v[164:167], v150 offset:2048
	ds_read_b128 v[180:183], v150 offset:3072
	v_add_u32_e32 v150, s5, v153
	ds_read_b128 v[184:187], v150
	ds_read_b128 v[188:191], v150 offset:1024
	ds_read_b128 v[192:195], v150 offset:2048
	ds_read_b128 v[196:199], v150 offset:3072
	v_lshl_add_u64 v[150:151], s[56:57], 0, v[146:147]
	s_add_i32 m0, s66, 0xc000
	ds_read_b128 v[200:203], v154
	ds_read_b128 v[204:207], v154 offset:1024
	ds_read_b128 v[208:211], v154 offset:2048
	ds_read_b128 v[212:215], v154 offset:3072
	ds_read_b128 v[216:219], v154 offset:4096
	ds_read_b128 v[220:223], v154 offset:5120
	ds_read_b128 v[224:227], v154 offset:6144
	ds_read_b128 v[228:231], v154 offset:7168
	global_load_lds_dwordx4 v[150:151], off
	v_lshl_add_u64 v[150:151], s[56:57], 0, v[148:149]
	s_add_i32 m0, s66, 0xe000
	s_nop 0
	global_load_lds_dwordx4 v[150:151], off
	s_waitcnt vmcnt(8)
	s_waitcnt lgkmcnt(0)
	s_setprio 1
	s_barrier
	v_mfma_f32_16x16x32_bf16 v[124:127], v[156:159], v[200:203], v[124:127]
	v_mfma_f32_16x16x32_bf16 v[116:119], v[164:167], v[200:203], v[116:119]
	v_mfma_f32_16x16x32_bf16 v[108:111], v[156:159], v[208:211], v[108:111]
	v_mfma_f32_16x16x32_bf16 v[100:103], v[164:167], v[208:211], v[100:103]
	v_mfma_f32_16x16x32_bf16 v[92:95], v[156:159], v[216:219], v[92:95]
	v_mfma_f32_16x16x32_bf16 v[84:87], v[164:167], v[216:219], v[84:87]
	v_mfma_f32_16x16x32_bf16 v[76:79], v[156:159], v[224:227], v[76:79]
	v_mfma_f32_16x16x32_bf16 v[68:71], v[164:167], v[224:227], v[68:71]
	v_mfma_f32_16x16x32_bf16 v[124:127], v[160:163], v[204:207], v[124:127]
	v_mfma_f32_16x16x32_bf16 v[116:119], v[180:183], v[204:207], v[116:119]
	v_mfma_f32_16x16x32_bf16 v[108:111], v[160:163], v[212:215], v[108:111]
	v_mfma_f32_16x16x32_bf16 v[100:103], v[180:183], v[212:215], v[100:103]
	v_mfma_f32_16x16x32_bf16 v[92:95], v[160:163], v[220:223], v[92:95]
	v_mfma_f32_16x16x32_bf16 v[84:87], v[180:183], v[220:223], v[84:87]
	v_mfma_f32_16x16x32_bf16 v[76:79], v[160:163], v[228:231], v[76:79]
	v_mfma_f32_16x16x32_bf16 v[68:71], v[180:183], v[228:231], v[68:71]
	s_setprio 0
	s_setprio 1
	v_mfma_f32_16x16x32_bf16 v[120:123], v[184:187], v[200:203], v[120:123]
	v_mfma_f32_16x16x32_bf16 v[112:115], v[192:195], v[200:203], v[112:115]
	v_mfma_f32_16x16x32_bf16 v[104:107], v[184:187], v[208:211], v[104:107]
	v_mfma_f32_16x16x32_bf16 v[96:99], v[192:195], v[208:211], v[96:99]
	v_mfma_f32_16x16x32_bf16 v[88:91], v[184:187], v[216:219], v[88:91]
	v_mfma_f32_16x16x32_bf16 v[80:83], v[192:195], v[216:219], v[80:83]
	v_mfma_f32_16x16x32_bf16 v[72:75], v[184:187], v[224:227], v[72:75]
	v_mfma_f32_16x16x32_bf16 v[64:67], v[192:195], v[224:227], v[64:67]
	v_mfma_f32_16x16x32_bf16 v[120:123], v[188:191], v[204:207], v[120:123]
	v_mfma_f32_16x16x32_bf16 v[112:115], v[196:199], v[204:207], v[112:115]
	v_mfma_f32_16x16x32_bf16 v[104:107], v[188:191], v[212:215], v[104:107]
	v_mfma_f32_16x16x32_bf16 v[96:99], v[196:199], v[212:215], v[96:99]
	v_mfma_f32_16x16x32_bf16 v[88:91], v[188:191], v[220:223], v[88:91]
	v_mfma_f32_16x16x32_bf16 v[80:83], v[196:199], v[220:223], v[80:83]
	s_setprio 2
	s_barrier
	v_mfma_f32_16x16x32_bf16 v[72:75], v[188:191], v[228:231], v[72:75]
	v_mfma_f32_16x16x32_bf16 v[64:67], v[196:199], v[228:231], v[64:67]
	s_setprio 0
	s_add_i32 s9, s10, s63
	v_lshl_add_u64 v[150:151], s[58:59], 0, v[142:143]
	s_mov_b32 m0, s9
	ds_read_b128 v[200:203], v154 offset:16384
	ds_read_b128 v[204:207], v154 offset:17408
	ds_read_b128 v[208:211], v154 offset:18432
	ds_read_b128 v[212:215], v154 offset:19456
	ds_read_b128 v[216:219], v154 offset:20480
	ds_read_b128 v[220:223], v154 offset:21504
	ds_read_b128 v[224:227], v154 offset:22528
	ds_read_b128 v[228:231], v154 offset:23552
	global_load_lds_dwordx4 v[150:151], off
	s_add_i32 m0, s9, 0x2000
	s_add_u32 s10, s58, 0x40000
	v_lshl_add_u64 v[232:233], s[58:59], 0, v[138:139]
	s_addc_u32 s11, s59, 0
	s_add_i32 s5, s5, s63
	global_load_lds_dwordx4 v[232:233], off
	v_lshl_add_u64 v[234:235], s[10:11], 0, v[142:143]
	s_mov_b32 m0, s5
	v_lshl_add_u64 v[236:237], s[60:61], 0, v[140:141]
	global_load_lds_dwordx4 v[234:235], off
	v_lshl_add_u64 v[234:235], s[10:11], 0, v[138:139]
	s_add_i32 m0, s5, 0x2000
	s_nop 0
	global_load_lds_dwordx4 v[234:235], off
	v_lshl_add_u64 v[234:235], s[60:61], 0, v[144:145]
	s_mov_b32 m0, s66
	s_nop 0
	global_load_lds_dwordx4 v[234:235], off
	s_mov_b32 m0, s67
	s_nop 0
	global_load_lds_dwordx4 v[236:237], off
	s_waitcnt vmcnt(8)
	s_waitcnt lgkmcnt(0)
	s_setprio 1
	s_barrier
; #define PG8_STAGE(bufoff, gbase, voff) do { _Pragma("unroll") for (int _i = 0; _i < 2; ++_i) \
;         __builtin_amdgcn_global_load_lds((const unsigned*)((const char*)(gbase) + (voff)[_i]), (LAS unsigned*)(lds + (bufoff) + ldsw + _i * 8192), 16, 0, 0); } while (0)
; #define PG8_LDA(dst, b, h) do { _Pragma("unroll") for (int m = 0; m < 4; ++m) _Pragma("unroll") for (int k = 0; k < 2; ++k) dst[m][k] = *(const LAS bf16x8*)(lds + PG8_SA(b, h) + aoff + m * 2048 + k * 1024); } while (0)
; #define PG8_LDB(dst, b, h) do { _Pragma("unroll") for (int n = 0; n < 2; ++n) _Pragma("unroll") for (int k = 0; k < 2; ++k) dst[n][k] = *(const LAS bf16x8*)(lds + PG8_SB(b, h) + boff + n * 2048 + k * 1024); } while (0)
; #define PG8_MMA(ai, bj, At, Bt) do { __builtin_amdgcn_s_setprio(1); _Pragma("unroll") for (int m = 0; m < 4; ++m) _Pragma("unroll") for (int n = 0; n < 2; ++n) _Pragma("unroll") for (int k = 0; k < 2; ++k) \
;         acc[ai][bj][m][n] = __builtin_amdgcn_mfma_f32_16x16x32_bf16(Bt[n][k], At[m][k], acc[ai][bj][m][n], 0, 0, 0); __builtin_amdgcn_s_setprio(0); } while (0)
; #define PG8_WAIT_V(n) asm volatile("s_waitcnt vmcnt(" #n ")" ::: "memory")
; #define PG8_WAIT_L(n) asm volatile("s_waitcnt lgkmcnt(" #n ")" ::: "memory")
; #define PG8_BAR __builtin_amdgcn_s_barrier()
; #define PG8_SCHED __builtin_amdgcn_sched_barrier(0)
; template <class Epi, class Sched>
; __device__ __forceinline__ void gemm_phase(LAS unsigned char* lds, const int K, const Sched& S, const Epi& E) {
;     ...
;             PG8_WAIT_V(8); PG8_WAIT_L(0); PG8_BAR; PG8_MMA(1, 0, At, B0); PG8_MMA(1, 1, At, B1); PG8_BAR; PG8_SCHED;
;             PG8_LDB(B0, 1, 0); PG8_LDB(B1, 1, 1); PG8_SCHED; PG8_LDA(At, 1, 0); PG8_STAGE(PG8_SA(0, 1), a2 + hstep, voffA);
;             PG8_WAIT_V(8); PG8_WAIT_L(0); PG8_BAR; PG8_MMA(0, 0, At, B0); PG8_MMA(0, 1, At, B1); PG8_BAR; PG8_SCHED;
	v_mfma_f32_16x16x32_bf16 v[60:63], v[156:159], v[200:203], v[60:63]
	v_mfma_f32_16x16x32_bf16 v[52:55], v[164:167], v[200:203], v[52:55]
	v_mfma_f32_16x16x32_bf16 v[44:47], v[156:159], v[208:211], v[44:47]
	v_mfma_f32_16x16x32_bf16 v[36:39], v[164:167], v[208:211], v[36:39]
	v_mfma_f32_16x16x32_bf16 v[28:31], v[156:159], v[216:219], v[28:31]
	v_mfma_f32_16x16x32_bf16 v[20:23], v[164:167], v[216:219], v[20:23]
	v_mfma_f32_16x16x32_bf16 v[12:15], v[156:159], v[224:227], v[12:15]
	v_mfma_f32_16x16x32_bf16 v[4:7], v[164:167], v[224:227], v[4:7]
	v_mfma_f32_16x16x32_bf16 v[60:63], v[160:163], v[204:207], v[60:63]
	v_mfma_f32_16x16x32_bf16 v[52:55], v[180:183], v[204:207], v[52:55]
	v_mfma_f32_16x16x32_bf16 v[44:47], v[160:163], v[212:215], v[44:47]
	v_mfma_f32_16x16x32_bf16 v[36:39], v[180:183], v[212:215], v[36:39]
	v_mfma_f32_16x16x32_bf16 v[28:31], v[160:163], v[220:223], v[28:31]
	v_mfma_f32_16x16x32_bf16 v[20:23], v[180:183], v[220:223], v[20:23]
	v_mfma_f32_16x16x32_bf16 v[12:15], v[160:163], v[228:231], v[12:15]
	v_mfma_f32_16x16x32_bf16 v[4:7], v[180:183], v[228:231], v[4:7]
	s_setprio 0
	s_setprio 1
	v_mfma_f32_16x16x32_bf16 v[56:59], v[184:187], v[200:203], v[56:59]
	v_mfma_f32_16x16x32_bf16 v[48:51], v[192:195], v[200:203], v[48:51]
	v_mfma_f32_16x16x32_bf16 v[40:43], v[184:187], v[208:211], v[40:43]
	v_mfma_f32_16x16x32_bf16 v[32:35], v[192:195], v[208:211], v[32:35]
	v_mfma_f32_16x16x32_bf16 v[24:27], v[184:187], v[216:219], v[24:27]
	v_mfma_f32_16x16x32_bf16 v[16:19], v[192:195], v[216:219], v[16:19]
	v_mfma_f32_16x16x32_bf16 v[8:11], v[184:187], v[224:227], v[8:11]
	v_mfma_f32_16x16x32_bf16 v[0:3], v[192:195], v[224:227], v[0:3]
	v_mfma_f32_16x16x32_bf16 v[56:59], v[188:191], v[204:207], v[56:59]
	v_mfma_f32_16x16x32_bf16 v[48:51], v[196:199], v[204:207], v[48:51]
	v_mfma_f32_16x16x32_bf16 v[40:43], v[188:191], v[212:215], v[40:43]
	v_mfma_f32_16x16x32_bf16 v[32:35], v[196:199], v[212:215], v[32:35]
	v_mfma_f32_16x16x32_bf16 v[24:27], v[188:191], v[220:223], v[24:27]
	v_mfma_f32_16x16x32_bf16 v[16:19], v[196:199], v[220:223], v[16:19]
	s_setprio 2
	s_barrier
	v_mfma_f32_16x16x32_bf16 v[8:11], v[188:191], v[228:231], v[8:11]
	v_mfma_f32_16x16x32_bf16 v[0:3], v[196:199], v[228:231], v[0:3]
	s_setprio 0
	s_add_i32 s5, 0, 0x18000
	v_add_u32_e32 v155, s5, v153
	s_add_i32 s9, 0, 0x1c000
	ds_read_b128 v[156:159], v155
	ds_read_b128 v[160:163], v155 offset:1024
	ds_read_b128 v[164:167], v155 offset:2048
	ds_read_b128 v[180:183], v155 offset:3072
	v_add_u32_e32 v155, s9, v153
	ds_read_b128 v[184:187], v155
	ds_read_b128 v[188:191], v155 offset:1024
	ds_read_b128 v[192:195], v155 offset:2048
	ds_read_b128 v[196:199], v155 offset:3072
	s_add_u32 s10, s60, 0x40000
	s_addc_u32 s11, s61, 0
	s_mov_b32 m0, s68
	v_lshl_add_u64 v[238:239], s[10:11], 0, v[144:145]
	ds_read_b128 v[200:203], v154 offset:32768
	ds_read_b128 v[204:207], v154 offset:33792
	ds_read_b128 v[208:211], v154 offset:34816
	ds_read_b128 v[212:215], v154 offset:35840
	ds_read_b128 v[216:219], v154 offset:36864
	ds_read_b128 v[220:223], v154 offset:37888
	ds_read_b128 v[224:227], v154 offset:38912
	ds_read_b128 v[228:231], v154 offset:39936
	global_load_lds_dwordx4 v[238:239], off
	v_lshl_add_u64 v[238:239], s[10:11], 0, v[140:141]
	s_mov_b32 m0, s69
	s_nop 0
	global_load_lds_dwordx4 v[238:239], off
	s_waitcnt vmcnt(8)
	s_waitcnt lgkmcnt(0)
	s_setprio 1
	s_barrier
	v_mfma_f32_16x16x32_bf16 v[124:127], v[156:159], v[200:203], v[124:127]
	v_mfma_f32_16x16x32_bf16 v[116:119], v[164:167], v[200:203], v[116:119]
	v_mfma_f32_16x16x32_bf16 v[108:111], v[156:159], v[208:211], v[108:111]
	v_mfma_f32_16x16x32_bf16 v[100:103], v[164:167], v[208:211], v[100:103]
	v_mfma_f32_16x16x32_bf16 v[92:95], v[156:159], v[216:219], v[92:95]
	v_mfma_f32_16x16x32_bf16 v[84:87], v[164:167], v[216:219], v[84:87]
	v_mfma_f32_16x16x32_bf16 v[76:79], v[156:159], v[224:227], v[76:79]
	v_mfma_f32_16x16x32_bf16 v[68:71], v[164:167], v[224:227], v[68:71]
	v_mfma_f32_16x16x32_bf16 v[124:127], v[160:163], v[204:207], v[124:127]
	v_mfma_f32_16x16x32_bf16 v[116:119], v[180:183], v[204:207], v[116:119]
	v_mfma_f32_16x16x32_bf16 v[108:111], v[160:163], v[212:215], v[108:111]
	v_mfma_f32_16x16x32_bf16 v[100:103], v[180:183], v[212:215], v[100:103]
	v_mfma_f32_16x16x32_bf16 v[92:95], v[160:163], v[220:223], v[92:95]
	v_mfma_f32_16x16x32_bf16 v[84:87], v[180:183], v[220:223], v[84:87]
	v_mfma_f32_16x16x32_bf16 v[76:79], v[160:163], v[228:231], v[76:79]
	v_mfma_f32_16x16x32_bf16 v[68:71], v[180:183], v[228:231], v[68:71]
	s_setprio 0
	s_setprio 1
	v_mfma_f32_16x16x32_bf16 v[120:123], v[184:187], v[200:203], v[120:123]
	v_mfma_f32_16x16x32_bf16 v[112:115], v[192:195], v[200:203], v[112:115]
	v_mfma_f32_16x16x32_bf16 v[104:107], v[184:187], v[208:211], v[104:107]
	v_mfma_f32_16x16x32_bf16 v[96:99], v[192:195], v[208:211], v[96:99]
	v_mfma_f32_16x16x32_bf16 v[88:91], v[184:187], v[216:219], v[88:91]
	v_mfma_f32_16x16x32_bf16 v[80:83], v[192:195], v[216:219], v[80:83]
	v_mfma_f32_16x16x32_bf16 v[72:75], v[184:187], v[224:227], v[72:75]
	v_mfma_f32_16x16x32_bf16 v[64:67], v[192:195], v[224:227], v[64:67]
	v_mfma_f32_16x16x32_bf16 v[120:123], v[188:191], v[204:207], v[120:123]
	v_mfma_f32_16x16x32_bf16 v[112:115], v[196:199], v[204:207], v[112:115]
	v_mfma_f32_16x16x32_bf16 v[104:107], v[188:191], v[212:215], v[104:107]
	v_mfma_f32_16x16x32_bf16 v[96:99], v[196:199], v[212:215], v[96:99]
	v_mfma_f32_16x16x32_bf16 v[88:91], v[188:191], v[220:223], v[88:91]
	v_mfma_f32_16x16x32_bf16 v[80:83], v[196:199], v[220:223], v[80:83]
	s_setprio 2
	s_barrier
; #define PG8_STAGE(bufoff, gbase, voff) do { _Pragma("unroll") for (int _i = 0; _i < 2; ++_i) \
;         __builtin_amdgcn_global_load_lds((const unsigned*)((const char*)(gbase) + (voff)[_i]), (LAS unsigned*)(lds + (bufoff) + ldsw + _i * 8192), 16, 0, 0); } while (0)
; #define PG8_LDA(dst, b, h) do { _Pragma("unroll") for (int m = 0; m < 4; ++m) _Pragma("unroll") for (int k = 0; k < 2; ++k) dst[m][k] = *(const LAS bf16x8*)(lds + PG8_SA(b, h) + aoff + m * 2048 + k * 1024); } while (0)
; #define PG8_MMA(ai, bj, At, Bt) do { __builtin_amdgcn_s_setprio(1); _Pragma("unroll") for (int m = 0; m < 4; ++m) _Pragma("unroll") for (int n = 0; n < 2; ++n) _Pragma("unroll") for (int k = 0; k < 2; ++k) \
;         acc[ai][bj][m][n] = __builtin_amdgcn_mfma_f32_16x16x32_bf16(Bt[n][k], At[m][k], acc[ai][bj][m][n], 0, 0, 0); __builtin_amdgcn_s_setprio(0); } while (0)
; #define PG8_WAIT_V(n) asm volatile("s_waitcnt vmcnt(" #n ")" ::: "memory")
; #define PG8_WAIT_L(n) asm volatile("s_waitcnt lgkmcnt(" #n ")" ::: "memory")
; #define PG8_BAR __builtin_amdgcn_s_barrier()
; #define PG8_SCHED __builtin_amdgcn_sched_barrier(0)
; template <class Epi, class Sched>
; __device__ __forceinline__ void gemm_phase(LAS unsigned char* lds, const int K, const Sched& S, const Epi& E) {
;     ...
;             PG8_WAIT_V(8); PG8_WAIT_L(0); PG8_BAR; PG8_MMA(0, 0, At, B0); PG8_MMA(0, 1, At, B1); PG8_BAR; PG8_SCHED;
;             PG8_LDA(At, 1, 1); PG8_STAGE(PG8_SB(1, 0), b3, voffB); PG8_STAGE(PG8_SB(1, 1), b3 + hstep, voffB); PG8_STAGE(PG8_SA(1, 0), a3, voffA);
;             PG8_WAIT_V(8); PG8_WAIT_L(0); PG8_BAR; PG8_MMA(1, 0, At, B0); PG8_MMA(1, 1, At, B1); PG8_BAR; PG8_SCHED;
;         }
;         if (wr == 0) PG8_BAR;
	v_mfma_f32_16x16x32_bf16 v[72:75], v[188:191], v[228:231], v[72:75]
	v_mfma_f32_16x16x32_bf16 v[64:67], v[196:199], v[228:231], v[64:67]
	s_setprio 0
	s_add_i32 s5, s5, s63
	v_lshl_add_u64 v[150:151], v[150:151], 0, s[36:37]
	s_mov_b32 m0, s5
	ds_read_b128 v[200:203], v154 offset:49152
	ds_read_b128 v[204:207], v154 offset:50176
	ds_read_b128 v[208:211], v154 offset:51200
	ds_read_b128 v[212:215], v154 offset:52224
	ds_read_b128 v[216:219], v154 offset:53248
	ds_read_b128 v[220:223], v154 offset:54272
	ds_read_b128 v[224:227], v154 offset:55296
	ds_read_b128 v[228:231], v154 offset:56320
	global_load_lds_dwordx4 v[150:151], off
	s_add_i32 m0, s5, 0x2000
	s_add_u32 s10, s58, 0x40080
	v_lshl_add_u64 v[150:151], v[232:233], 0, s[36:37]
	s_addc_u32 s11, s59, 0
	s_add_i32 s5, s9, s63
	global_load_lds_dwordx4 v[150:151], off
	v_lshl_add_u64 v[150:151], s[10:11], 0, v[142:143]
	s_mov_b32 m0, s5
	s_nop 0
	global_load_lds_dwordx4 v[150:151], off
	v_lshl_add_u64 v[150:151], s[10:11], 0, v[138:139]
	s_add_i32 m0, s5, 0x2000
	s_nop 0
	global_load_lds_dwordx4 v[150:151], off
	v_lshl_add_u64 v[150:151], v[234:235], 0, s[36:37]
	s_mov_b32 m0, s70
	s_nop 0
	global_load_lds_dwordx4 v[150:151], off
	v_lshl_add_u64 v[150:151], v[236:237], 0, s[36:37]
	s_mov_b32 m0, s71
	s_nop 0
	global_load_lds_dwordx4 v[150:151], off
	s_waitcnt vmcnt(8)
	s_waitcnt lgkmcnt(0)
	s_setprio 1
	s_barrier
	v_mfma_f32_16x16x32_bf16 v[60:63], v[156:159], v[200:203], v[60:63]
	v_mfma_f32_16x16x32_bf16 v[52:55], v[164:167], v[200:203], v[52:55]
	v_mfma_f32_16x16x32_bf16 v[44:47], v[156:159], v[208:211], v[44:47]
	v_mfma_f32_16x16x32_bf16 v[36:39], v[164:167], v[208:211], v[36:39]
	v_mfma_f32_16x16x32_bf16 v[28:31], v[156:159], v[216:219], v[28:31]
	v_mfma_f32_16x16x32_bf16 v[20:23], v[164:167], v[216:219], v[20:23]
	v_mfma_f32_16x16x32_bf16 v[12:15], v[156:159], v[224:227], v[12:15]
	v_mfma_f32_16x16x32_bf16 v[4:7], v[164:167], v[224:227], v[4:7]
	v_mfma_f32_16x16x32_bf16 v[60:63], v[160:163], v[204:207], v[60:63]
	v_mfma_f32_16x16x32_bf16 v[52:55], v[180:183], v[204:207], v[52:55]
	v_mfma_f32_16x16x32_bf16 v[44:47], v[160:163], v[212:215], v[44:47]
	v_mfma_f32_16x16x32_bf16 v[36:39], v[180:183], v[212:215], v[36:39]
	v_mfma_f32_16x16x32_bf16 v[28:31], v[160:163], v[220:223], v[28:31]
	v_mfma_f32_16x16x32_bf16 v[20:23], v[180:183], v[220:223], v[20:23]
	v_mfma_f32_16x16x32_bf16 v[12:15], v[160:163], v[228:231], v[12:15]
	v_mfma_f32_16x16x32_bf16 v[4:7], v[180:183], v[228:231], v[4:7]
	s_setprio 0
	s_setprio 1
	v_mfma_f32_16x16x32_bf16 v[56:59], v[184:187], v[200:203], v[56:59]
	v_mfma_f32_16x16x32_bf16 v[48:51], v[192:195], v[200:203], v[48:51]
	v_mfma_f32_16x16x32_bf16 v[40:43], v[184:187], v[208:211], v[40:43]
	v_mfma_f32_16x16x32_bf16 v[32:35], v[192:195], v[208:211], v[32:35]
	v_mfma_f32_16x16x32_bf16 v[24:27], v[184:187], v[216:219], v[24:27]
	v_mfma_f32_16x16x32_bf16 v[16:19], v[192:195], v[216:219], v[16:19]
	v_mfma_f32_16x16x32_bf16 v[8:11], v[184:187], v[224:227], v[8:11]
	v_mfma_f32_16x16x32_bf16 v[0:3], v[192:195], v[224:227], v[0:3]
	v_mfma_f32_16x16x32_bf16 v[56:59], v[188:191], v[204:207], v[56:59]
	v_mfma_f32_16x16x32_bf16 v[48:51], v[196:199], v[204:207], v[48:51]
	v_mfma_f32_16x16x32_bf16 v[40:43], v[188:191], v[212:215], v[40:43]
	v_mfma_f32_16x16x32_bf16 v[32:35], v[196:199], v[212:215], v[32:35]
	v_mfma_f32_16x16x32_bf16 v[24:27], v[188:191], v[220:223], v[24:27]
	v_mfma_f32_16x16x32_bf16 v[16:19], v[196:199], v[220:223], v[16:19]
	s_setprio 2
	s_barrier
	v_mfma_f32_16x16x32_bf16 v[8:11], v[188:191], v[228:231], v[8:11]
	v_mfma_f32_16x16x32_bf16 v[0:3], v[196:199], v[228:231], v[0:3]
	s_setprio 0
	s_add_i32 s4, s4, 2
	s_add_u32 s56, s56, 0x100
	s_addc_u32 s57, s57, 0
	s_add_u32 s1, s1, 0x100
	s_addc_u32 s2, s2, 0
	s_cmp_gt_u32 s4, 13
	s_cbranch_scc0 .LBB0_963
	s_and_b64 vcc, exec, s[46:47]
	s_cbranch_vccz .LBB0_966
	s_barrier

; #define PG8_STAGE(bufoff, gbase, voff) do { _Pragma("unroll") for (int _i = 0; _i < 2; ++_i) \
;         __builtin_amdgcn_global_load_lds((const unsigned*)((const char*)(gbase) + (voff)[_i]), (LAS unsigned*)(lds + (bufoff) + ldsw + _i * 8192), 16, 0, 0); } while (0)
; #define PG8_LDA(dst, b, h) do { _Pragma("unroll") for (int m = 0; m < 4; ++m) _Pragma("unroll") for (int k = 0; k < 2; ++k) dst[m][k] = *(const LAS bf16x8*)(lds + PG8_SA(b, h) + aoff + m * 2048 + k * 1024); } while (0)
; #define PG8_LDB(dst, b, h) do { _Pragma("unroll") for (int n = 0; n < 2; ++n) _Pragma("unroll") for (int k = 0; k < 2; ++k) dst[n][k] = *(const LAS bf16x8*)(lds + PG8_SB(b, h) + boff + n * 2048 + k * 1024); } while (0)
; #define PG8_MMA(ai, bj, At, Bt) do { __builtin_amdgcn_s_setprio(1); _Pragma("unroll") for (int m = 0; m < 4; ++m) _Pragma("unroll") for (int n = 0; n < 2; ++n) _Pragma("unroll") for (int k = 0; k < 2; ++k) \
;         acc[ai][bj][m][n] = __builtin_amdgcn_mfma_f32_16x16x32_bf16(Bt[n][k], At[m][k], acc[ai][bj][m][n], 0, 0, 0); __builtin_amdgcn_s_setprio(0); } while (0)
; #define PG8_WAIT_V(n) asm volatile("s_waitcnt vmcnt(" #n ")" ::: "memory")
; #define PG8_WAIT_L(n) asm volatile("s_waitcnt lgkmcnt(" #n ")" ::: "memory")
; #define PG8_BAR __builtin_amdgcn_s_barrier()
; #define PG8_SCHED __builtin_amdgcn_sched_barrier(0)
; template <class Epi, class Sched>
; __device__ __forceinline__ void gemm_phase(LAS unsigned char* lds, const int K, const Sched& S, const Epi& E) {
;     ...
;         for (int t = 0; t < nt; t += 2) {
;             const bool last = (t == nt - 2);
;             const char* a1 = cA + (size_t)(t + 1) * kstep;
;             const char* a2 = last ? nA : cA + (size_t)(t + 2) * kstep; const char* b2 = last ? nB : cB + (size_t)(t + 2) * kstep;
;             const char* a3 = a2 + kstep; const char* b3 = b2 + kstep;
;             PG8_LDB(B0, 0, 0); PG8_LDB(B1, 0, 1); PG8_SCHED; PG8_LDA(At, 0, 0); PG8_STAGE(PG8_SA(1, 1), a1 + hstep, voffA);
;             PG8_WAIT_V(8); PG8_WAIT_L(0); PG8_BAR; PG8_MMA(0, 0, At, B0); PG8_MMA(0, 1, At, B1); PG8_BAR; PG8_SCHED;
;             PG8_LDA(At, 0, 1); PG8_STAGE(PG8_SB(0, 0), b2, voffB); PG8_STAGE(PG8_SB(0, 1), b2 + hstep, voffB); PG8_STAGE(PG8_SA(0, 0), a2, voffA);
;             PG8_WAIT_V(8); PG8_WAIT_L(0); PG8_BAR; PG8_MMA(1, 0, At, B0); PG8_MMA(1, 1, At, B1); PG8_BAR; PG8_SCHED;
.LBB0_1073:
	s_add_i32 s13, s12, 2
	s_add_u32 s52, s8, 0x100
	s_addc_u32 s53, s9, 0
	s_add_i32 s14, 0, 0x10000
	s_cmp_eq_u32 s5, s12
	s_cselect_b32 s57, s0, s53
	s_cselect_b32 s56, s1, s52
	s_cselect_b32 s55, s2, s11
	s_cselect_b32 s54, s4, s10
	s_add_i32 s12, 0, 0x14000
	v_add_u32_e32 v158, s14, v164
	v_add_u32_e32 v162, s12, v164
	ds_read_b128 v[146:149], v158
	ds_read_b128 v[150:153], v158 offset:1024
	ds_read_b128 v[154:157], v158 offset:2048
	ds_read_b128 v[158:161], v158 offset:3072
	ds_read_b128 v[180:183], v162
	ds_read_b128 v[184:187], v162 offset:1024
	ds_read_b128 v[188:191], v162 offset:2048
	ds_read_b128 v[192:195], v162 offset:3072
	v_lshl_add_u64 v[162:163], s[8:9], 0, v[142:143]
	s_add_i32 m0, s61, 0xc000
	ds_read_b128 v[196:199], v166
	ds_read_b128 v[200:203], v166 offset:1024
	ds_read_b128 v[204:207], v166 offset:2048
	ds_read_b128 v[208:211], v166 offset:3072
	ds_read_b128 v[212:215], v166 offset:4096
	ds_read_b128 v[216:219], v166 offset:5120
	ds_read_b128 v[220:223], v166 offset:6144
	ds_read_b128 v[224:227], v166 offset:7168
	global_load_lds_dwordx4 v[162:163], off
	v_lshl_add_u64 v[162:163], s[8:9], 0, v[144:145]
	s_add_i32 m0, s61, 0xe000
	s_nop 0
	global_load_lds_dwordx4 v[162:163], off
	s_waitcnt vmcnt(8)
	s_waitcnt lgkmcnt(0)
	s_setprio 1
	s_barrier
	v_mfma_f32_16x16x32_bf16 v[124:127], v[146:149], v[196:199], v[124:127]
	v_mfma_f32_16x16x32_bf16 v[92:95], v[154:157], v[196:199], v[92:95]
	v_mfma_f32_16x16x32_bf16 v[120:123], v[146:149], v[204:207], v[120:123]
	v_mfma_f32_16x16x32_bf16 v[88:91], v[154:157], v[204:207], v[88:91]
	v_mfma_f32_16x16x32_bf16 v[116:119], v[146:149], v[212:215], v[116:119]
	v_mfma_f32_16x16x32_bf16 v[84:87], v[154:157], v[212:215], v[84:87]
	v_mfma_f32_16x16x32_bf16 v[112:115], v[146:149], v[220:223], v[112:115]
	v_mfma_f32_16x16x32_bf16 v[80:83], v[154:157], v[220:223], v[80:83]
	v_mfma_f32_16x16x32_bf16 v[124:127], v[150:153], v[200:203], v[124:127]
	v_mfma_f32_16x16x32_bf16 v[92:95], v[158:161], v[200:203], v[92:95]
	v_mfma_f32_16x16x32_bf16 v[120:123], v[150:153], v[208:211], v[120:123]
	v_mfma_f32_16x16x32_bf16 v[88:91], v[158:161], v[208:211], v[88:91]
	v_mfma_f32_16x16x32_bf16 v[116:119], v[150:153], v[216:219], v[116:119]
	v_mfma_f32_16x16x32_bf16 v[84:87], v[158:161], v[216:219], v[84:87]
	v_mfma_f32_16x16x32_bf16 v[112:115], v[150:153], v[224:227], v[112:115]
	v_mfma_f32_16x16x32_bf16 v[80:83], v[158:161], v[224:227], v[80:83]
	s_setprio 0
	s_setprio 1
	v_mfma_f32_16x16x32_bf16 v[60:63], v[180:183], v[196:199], v[60:63]
	v_mfma_f32_16x16x32_bf16 v[28:31], v[188:191], v[196:199], v[28:31]
	v_mfma_f32_16x16x32_bf16 v[56:59], v[180:183], v[204:207], v[56:59]
	v_mfma_f32_16x16x32_bf16 v[24:27], v[188:191], v[204:207], v[24:27]
	v_mfma_f32_16x16x32_bf16 v[52:55], v[180:183], v[212:215], v[52:55]
	v_mfma_f32_16x16x32_bf16 v[20:23], v[188:191], v[212:215], v[20:23]
	v_mfma_f32_16x16x32_bf16 v[48:51], v[180:183], v[220:223], v[48:51]
	v_mfma_f32_16x16x32_bf16 v[16:19], v[188:191], v[220:223], v[16:19]
	v_mfma_f32_16x16x32_bf16 v[60:63], v[184:187], v[200:203], v[60:63]
	v_mfma_f32_16x16x32_bf16 v[28:31], v[192:195], v[200:203], v[28:31]
	v_mfma_f32_16x16x32_bf16 v[56:59], v[184:187], v[208:211], v[56:59]
	v_mfma_f32_16x16x32_bf16 v[24:27], v[192:195], v[208:211], v[24:27]
	v_mfma_f32_16x16x32_bf16 v[52:55], v[184:187], v[216:219], v[52:55]
	v_mfma_f32_16x16x32_bf16 v[20:23], v[192:195], v[216:219], v[20:23]
	s_setprio 2
	s_barrier
	v_mfma_f32_16x16x32_bf16 v[48:51], v[184:187], v[224:227], v[48:51]
	v_mfma_f32_16x16x32_bf16 v[16:19], v[192:195], v[224:227], v[16:19]
	s_setprio 0
	s_add_i32 s8, s14, s60
	v_lshl_add_u64 v[162:163], s[54:55], 0, v[128:129]
	s_mov_b32 m0, s8
	ds_read_b128 v[196:199], v166 offset:16384
	ds_read_b128 v[200:203], v166 offset:17408
	ds_read_b128 v[204:207], v166 offset:18432
	ds_read_b128 v[208:211], v166 offset:19456
	ds_read_b128 v[212:215], v166 offset:20480
	ds_read_b128 v[216:219], v166 offset:21504
	ds_read_b128 v[220:223], v166 offset:22528
	ds_read_b128 v[224:227], v166 offset:23552
	global_load_lds_dwordx4 v[162:163], off
	s_add_i32 m0, s8, 0x2000
	s_add_u32 s8, s54, 0xb0000
	v_lshl_add_u64 v[228:229], s[54:55], 0, v[138:139]
	s_addc_u32 s9, s55, 0
	s_add_i32 s12, s12, s60
	global_load_lds_dwordx4 v[228:229], off
	v_lshl_add_u64 v[230:231], s[8:9], 0, v[128:129]
	s_mov_b32 m0, s12
	v_lshl_add_u64 v[232:233], s[56:57], 0, v[138:139]
	global_load_lds_dwordx4 v[230:231], off
	v_lshl_add_u64 v[230:231], s[8:9], 0, v[138:139]
	s_add_i32 m0, s12, 0x2000
	s_nop 0
	global_load_lds_dwordx4 v[230:231], off
	v_lshl_add_u64 v[230:231], s[56:57], 0, v[128:129]
	s_mov_b32 m0, s61
	s_nop 0
	global_load_lds_dwordx4 v[230:231], off
	s_mov_b32 m0, s63
	s_nop 0
	global_load_lds_dwordx4 v[232:233], off
	s_waitcnt vmcnt(8)
	s_waitcnt lgkmcnt(0)
	s_setprio 1
	s_barrier
; #define PG8_STAGE(bufoff, gbase, voff) do { _Pragma("unroll") for (int _i = 0; _i < 2; ++_i) \
;         __builtin_amdgcn_global_load_lds((const unsigned*)((const char*)(gbase) + (voff)[_i]), (LAS unsigned*)(lds + (bufoff) + ldsw + _i * 8192), 16, 0, 0); } while (0)
; #define PG8_LDA(dst, b, h) do { _Pragma("unroll") for (int m = 0; m < 4; ++m) _Pragma("unroll") for (int k = 0; k < 2; ++k) dst[m][k] = *(const LAS bf16x8*)(lds + PG8_SA(b, h) + aoff + m * 2048 + k * 1024); } while (0)
; #define PG8_LDB(dst, b, h) do { _Pragma("unroll") for (int n = 0; n < 2; ++n) _Pragma("unroll") for (int k = 0; k < 2; ++k) dst[n][k] = *(const LAS bf16x8*)(lds + PG8_SB(b, h) + boff + n * 2048 + k * 1024); } while (0)
; #define PG8_MMA(ai, bj, At, Bt) do { __builtin_amdgcn_s_setprio(1); _Pragma("unroll") for (int m = 0; m < 4; ++m) _Pragma("unroll") for (int n = 0; n < 2; ++n) _Pragma("unroll") for (int k = 0; k < 2; ++k) \
;         acc[ai][bj][m][n] = __builtin_amdgcn_mfma_f32_16x16x32_bf16(Bt[n][k], At[m][k], acc[ai][bj][m][n], 0, 0, 0); __builtin_amdgcn_s_setprio(0); } while (0)
; #define PG8_WAIT_V(n) asm volatile("s_waitcnt vmcnt(" #n ")" ::: "memory")
; #define PG8_WAIT_L(n) asm volatile("s_waitcnt lgkmcnt(" #n ")" ::: "memory")
; #define PG8_BAR __builtin_amdgcn_s_barrier()
; #define PG8_SCHED __builtin_amdgcn_sched_barrier(0)
; template <class Epi, class Sched>
; __device__ __forceinline__ void gemm_phase(LAS unsigned char* lds, const int K, const Sched& S, const Epi& E) {
;     ...
;             PG8_WAIT_V(8); PG8_WAIT_L(0); PG8_BAR; PG8_MMA(1, 0, At, B0); PG8_MMA(1, 1, At, B1); PG8_BAR; PG8_SCHED;
;             PG8_LDB(B0, 1, 0); PG8_LDB(B1, 1, 1); PG8_SCHED; PG8_LDA(At, 1, 0); PG8_STAGE(PG8_SA(0, 1), a2 + hstep, voffA);
;             PG8_WAIT_V(8); PG8_WAIT_L(0); PG8_BAR; PG8_MMA(0, 0, At, B0); PG8_MMA(0, 1, At, B1); PG8_BAR; PG8_SCHED;
	v_mfma_f32_16x16x32_bf16 v[108:111], v[146:149], v[196:199], v[108:111]
	v_mfma_f32_16x16x32_bf16 v[76:79], v[154:157], v[196:199], v[76:79]
	v_mfma_f32_16x16x32_bf16 v[104:107], v[146:149], v[204:207], v[104:107]
	v_mfma_f32_16x16x32_bf16 v[72:75], v[154:157], v[204:207], v[72:75]
	v_mfma_f32_16x16x32_bf16 v[100:103], v[146:149], v[212:215], v[100:103]
	v_mfma_f32_16x16x32_bf16 v[68:71], v[154:157], v[212:215], v[68:71]
	v_mfma_f32_16x16x32_bf16 v[96:99], v[146:149], v[220:223], v[96:99]
	v_mfma_f32_16x16x32_bf16 v[64:67], v[154:157], v[220:223], v[64:67]
	v_mfma_f32_16x16x32_bf16 v[108:111], v[150:153], v[200:203], v[108:111]
	v_mfma_f32_16x16x32_bf16 v[76:79], v[158:161], v[200:203], v[76:79]
	v_mfma_f32_16x16x32_bf16 v[104:107], v[150:153], v[208:211], v[104:107]
	v_mfma_f32_16x16x32_bf16 v[72:75], v[158:161], v[208:211], v[72:75]
	v_mfma_f32_16x16x32_bf16 v[100:103], v[150:153], v[216:219], v[100:103]
	v_mfma_f32_16x16x32_bf16 v[68:71], v[158:161], v[216:219], v[68:71]
	v_mfma_f32_16x16x32_bf16 v[96:99], v[150:153], v[224:227], v[96:99]
	v_mfma_f32_16x16x32_bf16 v[64:67], v[158:161], v[224:227], v[64:67]
	s_setprio 0
	s_setprio 1
	v_mfma_f32_16x16x32_bf16 v[44:47], v[180:183], v[196:199], v[44:47]
	v_mfma_f32_16x16x32_bf16 v[12:15], v[188:191], v[196:199], v[12:15]
	v_mfma_f32_16x16x32_bf16 v[40:43], v[180:183], v[204:207], v[40:43]
	v_mfma_f32_16x16x32_bf16 v[8:11], v[188:191], v[204:207], v[8:11]
	v_mfma_f32_16x16x32_bf16 v[36:39], v[180:183], v[212:215], v[36:39]
	v_mfma_f32_16x16x32_bf16 v[4:7], v[188:191], v[212:215], v[4:7]
	v_mfma_f32_16x16x32_bf16 v[32:35], v[180:183], v[220:223], v[32:35]
	v_mfma_f32_16x16x32_bf16 v[0:3], v[188:191], v[220:223], v[0:3]
	v_mfma_f32_16x16x32_bf16 v[44:47], v[184:187], v[200:203], v[44:47]
	v_mfma_f32_16x16x32_bf16 v[12:15], v[192:195], v[200:203], v[12:15]
	v_mfma_f32_16x16x32_bf16 v[40:43], v[184:187], v[208:211], v[40:43]
	v_mfma_f32_16x16x32_bf16 v[8:11], v[192:195], v[208:211], v[8:11]
	v_mfma_f32_16x16x32_bf16 v[36:39], v[184:187], v[216:219], v[36:39]
	v_mfma_f32_16x16x32_bf16 v[4:7], v[192:195], v[216:219], v[4:7]
	s_setprio 2
	s_barrier
	v_mfma_f32_16x16x32_bf16 v[32:35], v[184:187], v[224:227], v[32:35]
	v_mfma_f32_16x16x32_bf16 v[0:3], v[192:195], v[224:227], v[0:3]
	s_setprio 0
	s_add_i32 s12, 0, 0x18000
	s_add_i32 s14, 0, 0x1c000
	v_add_u32_e32 v158, s12, v164
	v_add_u32_e32 v167, s14, v164
	ds_read_b128 v[146:149], v158
	ds_read_b128 v[150:153], v158 offset:1024
	ds_read_b128 v[154:157], v158 offset:2048
	ds_read_b128 v[158:161], v158 offset:3072
	ds_read_b128 v[180:183], v167
	ds_read_b128 v[184:187], v167 offset:1024
	ds_read_b128 v[188:191], v167 offset:2048
	ds_read_b128 v[192:195], v167 offset:3072
	s_add_u32 s8, s56, 0xb0000
	s_addc_u32 s9, s57, 0
	s_mov_b32 m0, s64
	v_lshl_add_u64 v[234:235], s[8:9], 0, v[128:129]
	ds_read_b128 v[196:199], v166 offset:32768
	ds_read_b128 v[200:203], v166 offset:33792
	ds_read_b128 v[204:207], v166 offset:34816
	ds_read_b128 v[208:211], v166 offset:35840
	ds_read_b128 v[212:215], v166 offset:36864
	ds_read_b128 v[216:219], v166 offset:37888
	ds_read_b128 v[220:223], v166 offset:38912
	ds_read_b128 v[224:227], v166 offset:39936
	global_load_lds_dwordx4 v[234:235], off
	v_lshl_add_u64 v[234:235], s[8:9], 0, v[138:139]
	s_mov_b32 m0, s65
	s_nop 0
	global_load_lds_dwordx4 v[234:235], off
	s_waitcnt vmcnt(8)
	s_waitcnt lgkmcnt(0)
	s_setprio 1
	s_barrier
	v_mfma_f32_16x16x32_bf16 v[124:127], v[146:149], v[196:199], v[124:127]
	v_mfma_f32_16x16x32_bf16 v[92:95], v[154:157], v[196:199], v[92:95]
	v_mfma_f32_16x16x32_bf16 v[120:123], v[146:149], v[204:207], v[120:123]
	v_mfma_f32_16x16x32_bf16 v[88:91], v[154:157], v[204:207], v[88:91]
	v_mfma_f32_16x16x32_bf16 v[116:119], v[146:149], v[212:215], v[116:119]
	v_mfma_f32_16x16x32_bf16 v[84:87], v[154:157], v[212:215], v[84:87]
	v_mfma_f32_16x16x32_bf16 v[112:115], v[146:149], v[220:223], v[112:115]
	v_mfma_f32_16x16x32_bf16 v[80:83], v[154:157], v[220:223], v[80:83]
	v_mfma_f32_16x16x32_bf16 v[124:127], v[150:153], v[200:203], v[124:127]
	v_mfma_f32_16x16x32_bf16 v[92:95], v[158:161], v[200:203], v[92:95]
	v_mfma_f32_16x16x32_bf16 v[120:123], v[150:153], v[208:211], v[120:123]
	v_mfma_f32_16x16x32_bf16 v[88:91], v[158:161], v[208:211], v[88:91]
	v_mfma_f32_16x16x32_bf16 v[116:119], v[150:153], v[216:219], v[116:119]
	v_mfma_f32_16x16x32_bf16 v[84:87], v[158:161], v[216:219], v[84:87]
	v_mfma_f32_16x16x32_bf16 v[112:115], v[150:153], v[224:227], v[112:115]
	v_mfma_f32_16x16x32_bf16 v[80:83], v[158:161], v[224:227], v[80:83]
	s_setprio 0
	s_setprio 1
	v_mfma_f32_16x16x32_bf16 v[60:63], v[180:183], v[196:199], v[60:63]
	v_mfma_f32_16x16x32_bf16 v[28:31], v[188:191], v[196:199], v[28:31]
	v_mfma_f32_16x16x32_bf16 v[56:59], v[180:183], v[204:207], v[56:59]
	v_mfma_f32_16x16x32_bf16 v[24:27], v[188:191], v[204:207], v[24:27]
	v_mfma_f32_16x16x32_bf16 v[52:55], v[180:183], v[212:215], v[52:55]
	v_mfma_f32_16x16x32_bf16 v[20:23], v[188:191], v[212:215], v[20:23]
	v_mfma_f32_16x16x32_bf16 v[48:51], v[180:183], v[220:223], v[48:51]
	v_mfma_f32_16x16x32_bf16 v[16:19], v[188:191], v[220:223], v[16:19]
	v_mfma_f32_16x16x32_bf16 v[60:63], v[184:187], v[200:203], v[60:63]
	v_mfma_f32_16x16x32_bf16 v[28:31], v[192:195], v[200:203], v[28:31]
	v_mfma_f32_16x16x32_bf16 v[56:59], v[184:187], v[208:211], v[56:59]
	v_mfma_f32_16x16x32_bf16 v[24:27], v[192:195], v[208:211], v[24:27]
	v_mfma_f32_16x16x32_bf16 v[52:55], v[184:187], v[216:219], v[52:55]
	v_mfma_f32_16x16x32_bf16 v[20:23], v[192:195], v[216:219], v[20:23]
	s_setprio 2
	s_barrier
; #define PG8_STAGE(bufoff, gbase, voff) do { _Pragma("unroll") for (int _i = 0; _i < 2; ++_i) \
;         __builtin_amdgcn_global_load_lds((const unsigned*)((const char*)(gbase) + (voff)[_i]), (LAS unsigned*)(lds + (bufoff) + ldsw + _i * 8192), 16, 0, 0); } while (0)
; #define PG8_LDA(dst, b, h) do { _Pragma("unroll") for (int m = 0; m < 4; ++m) _Pragma("unroll") for (int k = 0; k < 2; ++k) dst[m][k] = *(const LAS bf16x8*)(lds + PG8_SA(b, h) + aoff + m * 2048 + k * 1024); } while (0)
; #define PG8_MMA(ai, bj, At, Bt) do { __builtin_amdgcn_s_setprio(1); _Pragma("unroll") for (int m = 0; m < 4; ++m) _Pragma("unroll") for (int n = 0; n < 2; ++n) _Pragma("unroll") for (int k = 0; k < 2; ++k) \
;         acc[ai][bj][m][n] = __builtin_amdgcn_mfma_f32_16x16x32_bf16(Bt[n][k], At[m][k], acc[ai][bj][m][n], 0, 0, 0); __builtin_amdgcn_s_setprio(0); } while (0)
; #define PG8_WAIT_V(n) asm volatile("s_waitcnt vmcnt(" #n ")" ::: "memory")
; #define PG8_WAIT_L(n) asm volatile("s_waitcnt lgkmcnt(" #n ")" ::: "memory")
; #define PG8_BAR __builtin_amdgcn_s_barrier()
; #define PG8_SCHED __builtin_amdgcn_sched_barrier(0)
; template <class Epi, class Sched>
; __device__ __forceinline__ void gemm_phase(LAS unsigned char* lds, const int K, const Sched& S, const Epi& E) {
;     ...
;             PG8_WAIT_V(8); PG8_WAIT_L(0); PG8_BAR; PG8_MMA(0, 0, At, B0); PG8_MMA(0, 1, At, B1); PG8_BAR; PG8_SCHED;
;             PG8_LDA(At, 1, 1); PG8_STAGE(PG8_SB(1, 0), b3, voffB); PG8_STAGE(PG8_SB(1, 1), b3 + hstep, voffB); PG8_STAGE(PG8_SA(1, 0), a3, voffA);
;             PG8_WAIT_V(8); PG8_WAIT_L(0); PG8_BAR; PG8_MMA(1, 0, At, B0); PG8_MMA(1, 1, At, B1); PG8_BAR; PG8_SCHED;
;         }
;         if (wr == 0) PG8_BAR;
	v_mfma_f32_16x16x32_bf16 v[48:51], v[184:187], v[224:227], v[48:51]
	v_mfma_f32_16x16x32_bf16 v[16:19], v[192:195], v[224:227], v[16:19]
	s_setprio 0
	s_add_i32 s8, s12, s60
	v_lshl_add_u64 v[162:163], v[162:163], 0, s[36:37]
	s_mov_b32 m0, s8
	ds_read_b128 v[196:199], v166 offset:49152
	ds_read_b128 v[200:203], v166 offset:50176
	ds_read_b128 v[204:207], v166 offset:51200
	ds_read_b128 v[208:211], v166 offset:52224
	ds_read_b128 v[212:215], v166 offset:53248
	ds_read_b128 v[216:219], v166 offset:54272
	ds_read_b128 v[220:223], v166 offset:55296
	ds_read_b128 v[224:227], v166 offset:56320
	global_load_lds_dwordx4 v[162:163], off
	s_add_i32 m0, s8, 0x2000
	s_add_u32 s8, s54, 0xb0080
	v_lshl_add_u64 v[162:163], v[228:229], 0, s[36:37]
	s_addc_u32 s9, s55, 0
	s_add_i32 s12, s14, s60
	global_load_lds_dwordx4 v[162:163], off
	v_lshl_add_u64 v[162:163], s[8:9], 0, v[128:129]
	s_mov_b32 m0, s12
	s_nop 0
	global_load_lds_dwordx4 v[162:163], off
	v_lshl_add_u64 v[162:163], s[8:9], 0, v[138:139]
	s_add_i32 m0, s12, 0x2000
	s_nop 0
	global_load_lds_dwordx4 v[162:163], off
	v_lshl_add_u64 v[162:163], v[230:231], 0, s[36:37]
	s_mov_b32 m0, s68
	s_nop 0
	global_load_lds_dwordx4 v[162:163], off
	v_lshl_add_u64 v[162:163], v[232:233], 0, s[36:37]
	s_mov_b32 m0, s69
	s_nop 0
	global_load_lds_dwordx4 v[162:163], off
	s_waitcnt vmcnt(8)
	s_waitcnt lgkmcnt(0)
	s_setprio 1
	s_barrier
	v_mfma_f32_16x16x32_bf16 v[108:111], v[146:149], v[196:199], v[108:111]
	v_mfma_f32_16x16x32_bf16 v[76:79], v[154:157], v[196:199], v[76:79]
	v_mfma_f32_16x16x32_bf16 v[104:107], v[146:149], v[204:207], v[104:107]
	v_mfma_f32_16x16x32_bf16 v[72:75], v[154:157], v[204:207], v[72:75]
	v_mfma_f32_16x16x32_bf16 v[100:103], v[146:149], v[212:215], v[100:103]
	v_mfma_f32_16x16x32_bf16 v[68:71], v[154:157], v[212:215], v[68:71]
	v_mfma_f32_16x16x32_bf16 v[96:99], v[146:149], v[220:223], v[96:99]
	v_mfma_f32_16x16x32_bf16 v[64:67], v[154:157], v[220:223], v[64:67]
	v_mfma_f32_16x16x32_bf16 v[108:111], v[150:153], v[200:203], v[108:111]
	v_mfma_f32_16x16x32_bf16 v[76:79], v[158:161], v[200:203], v[76:79]
	v_mfma_f32_16x16x32_bf16 v[104:107], v[150:153], v[208:211], v[104:107]
	v_mfma_f32_16x16x32_bf16 v[72:75], v[158:161], v[208:211], v[72:75]
	v_mfma_f32_16x16x32_bf16 v[100:103], v[150:153], v[216:219], v[100:103]
	v_mfma_f32_16x16x32_bf16 v[68:71], v[158:161], v[216:219], v[68:71]
	v_mfma_f32_16x16x32_bf16 v[96:99], v[150:153], v[224:227], v[96:99]
	v_mfma_f32_16x16x32_bf16 v[64:67], v[158:161], v[224:227], v[64:67]
	s_setprio 0
	s_setprio 1
	v_mfma_f32_16x16x32_bf16 v[44:47], v[180:183], v[196:199], v[44:47]
	v_mfma_f32_16x16x32_bf16 v[12:15], v[188:191], v[196:199], v[12:15]
	v_mfma_f32_16x16x32_bf16 v[40:43], v[180:183], v[204:207], v[40:43]
	v_mfma_f32_16x16x32_bf16 v[8:11], v[188:191], v[204:207], v[8:11]
	v_mfma_f32_16x16x32_bf16 v[36:39], v[180:183], v[212:215], v[36:39]
	v_mfma_f32_16x16x32_bf16 v[4:7], v[188:191], v[212:215], v[4:7]
	v_mfma_f32_16x16x32_bf16 v[32:35], v[180:183], v[220:223], v[32:35]
	v_mfma_f32_16x16x32_bf16 v[0:3], v[188:191], v[220:223], v[0:3]
	v_mfma_f32_16x16x32_bf16 v[44:47], v[184:187], v[200:203], v[44:47]
	v_mfma_f32_16x16x32_bf16 v[12:15], v[192:195], v[200:203], v[12:15]
	v_mfma_f32_16x16x32_bf16 v[40:43], v[184:187], v[208:211], v[40:43]
	v_mfma_f32_16x16x32_bf16 v[8:11], v[192:195], v[208:211], v[8:11]
	v_mfma_f32_16x16x32_bf16 v[36:39], v[184:187], v[216:219], v[36:39]
	v_mfma_f32_16x16x32_bf16 v[4:7], v[192:195], v[216:219], v[4:7]
	s_setprio 2
	s_barrier
	v_mfma_f32_16x16x32_bf16 v[32:35], v[184:187], v[224:227], v[32:35]
	v_mfma_f32_16x16x32_bf16 v[0:3], v[192:195], v[224:227], v[0:3]
	s_setprio 0
	s_add_u32 s10, s10, 0x100
	s_addc_u32 s11, s11, 0
	s_cmp_ge_i32 s13, s51
	s_mov_b64 s[8:9], s[52:53]
	s_mov_b32 s12, s13
	s_cbranch_scc0 .LBB0_1073
	s_and_b64 vcc, exec, s[40:41]
	s_cbranch_vccz .LBB0_1076
